# nt hint: + GLA prep loads and attention q / gate loads
# baseline (speedup 1.0000x reference)
.LBB0_804:
	s_or_b64 exec, exec, s[6:7]
	s_waitcnt lgkmcnt(0)
	v_add_u32_e32 v74, s71, v148
	ds_read_b128 v[66:69], v74
	ds_read_b128 v[70:73], v74 offset:32
	s_lshl_b64 s[6:7], s[28:29], 13
	s_add_u32 s4, s42, s6
	s_addc_u32 s5, s43, s7
	s_lshl_b32 s28, s69, 1
	s_add_u32 s4, s4, s28
	s_addc_u32 s5, s5, 0
	s_waitcnt lgkmcnt(1)
	v_rcp_f32_e32 v75, v66
	s_add_u32 s6, s0, s6
	s_addc_u32 s7, s1, s7
	v_rcp_f32_e32 v76, v67
	v_rcp_f32_e32 v77, v68
	v_rcp_f32_e32 v78, v69
	s_waitcnt lgkmcnt(0)
	v_rcp_f32_e32 v79, v70
	ds_read_b128 v[66:69], v74 offset:64
	v_rcp_f32_e32 v80, v71
	v_rcp_f32_e32 v81, v72
	v_rcp_f32_e32 v82, v73
	ds_read_b128 v[70:73], v74 offset:96
	v_mul_u32_u24_e32 v74, 0x440, v155
	s_add_u32 s6, s6, s28
	s_mulk_i32 s68, 0x2200
	v_lshl_or_b32 v74, v154, 1, v74
	s_addc_u32 s7, s7, 0
	s_waitcnt lgkmcnt(0)
	s_barrier
	s_add_i32 s28, s68, 0
	v_mul_f32_e32 v2, v2, v75
	v_add_u32_e32 v74, s28, v74
	v_cvt_pk_bf16_f32 v2, v2, v147
	ds_write_b16 v74, v2
	v_mul_f32_e32 v2, v50, v75
	v_cvt_pk_bf16_f32 v2, v2, v147
	ds_write_b16 v74, v2 offset:64
	v_mul_f32_e32 v2, v34, v75
	v_cvt_pk_bf16_f32 v2, v2, v147
	ds_write_b16 v74, v2 offset:128
	v_mul_f32_e32 v2, v18, v75
	v_cvt_pk_bf16_f32 v2, v2, v147
	ds_write_b16 v74, v2 offset:192
	v_mul_f32_e32 v2, v3, v76
	v_cvt_pk_bf16_f32 v2, v2, v147
	ds_write_b16 v74, v2 offset:272
	v_mul_f32_e32 v2, v51, v76
	v_cvt_pk_bf16_f32 v2, v2, v147
	ds_write_b16 v74, v2 offset:336
	v_mul_f32_e32 v2, v35, v76
	v_cvt_pk_bf16_f32 v2, v2, v147
	ds_write_b16 v74, v2 offset:400
	v_mul_f32_e32 v2, v19, v76
	v_cvt_pk_bf16_f32 v2, v2, v147
	ds_write_b16 v74, v2 offset:464
	v_mul_f32_e32 v2, v4, v77
	v_cvt_pk_bf16_f32 v2, v2, v147
	ds_write_b16 v74, v2 offset:544
	v_mul_f32_e32 v2, v52, v77
	v_cvt_pk_bf16_f32 v2, v2, v147
	ds_write_b16 v74, v2 offset:608
	v_mul_f32_e32 v2, v36, v77
	v_cvt_pk_bf16_f32 v2, v2, v147
	ds_write_b16 v74, v2 offset:672
	v_mul_f32_e32 v2, v20, v77
	v_cvt_pk_bf16_f32 v2, v2, v147
	ds_write_b16 v74, v2 offset:736
	v_mul_f32_e32 v2, v5, v78
	v_cvt_pk_bf16_f32 v2, v2, v147
	ds_write_b16 v74, v2 offset:816
	v_mul_f32_e32 v2, v53, v78
	v_cvt_pk_bf16_f32 v2, v2, v147
	ds_write_b16 v74, v2 offset:880
	v_mul_f32_e32 v2, v37, v78
	v_cvt_pk_bf16_f32 v2, v2, v147
	ds_write_b16 v74, v2 offset:944
	v_mul_f32_e32 v2, v21, v78
	v_cvt_pk_bf16_f32 v2, v2, v147
	ds_write_b16 v74, v2 offset:1008
	v_mul_f32_e32 v2, v6, v79
	v_cvt_pk_bf16_f32 v2, v2, v147
	ds_write_b16 v74, v2 offset:2176
	v_mul_f32_e32 v2, v54, v79
	v_cvt_pk_bf16_f32 v2, v2, v147
	ds_write_b16 v74, v2 offset:2240
	v_mul_f32_e32 v2, v38, v79
	v_cvt_pk_bf16_f32 v2, v2, v147
	ds_write_b16 v74, v2 offset:2304
	v_mul_f32_e32 v2, v22, v79
	v_cvt_pk_bf16_f32 v2, v2, v147
	ds_write_b16 v74, v2 offset:2368
	v_mul_f32_e32 v2, v7, v80
	v_cvt_pk_bf16_f32 v2, v2, v147
	ds_write_b16 v74, v2 offset:2448
	v_mul_f32_e32 v2, v55, v80
	v_cvt_pk_bf16_f32 v2, v2, v147
	ds_write_b16 v74, v2 offset:2512
	v_mul_f32_e32 v2, v39, v80
	v_cvt_pk_bf16_f32 v2, v2, v147
	ds_write_b16 v74, v2 offset:2576
	v_mul_f32_e32 v2, v23, v80
	v_cvt_pk_bf16_f32 v2, v2, v147
	ds_write_b16 v74, v2 offset:2640
	v_mul_f32_e32 v2, v8, v81
	v_cvt_pk_bf16_f32 v2, v2, v147
	ds_write_b16 v74, v2 offset:2720
	v_mul_f32_e32 v2, v56, v81
	v_cvt_pk_bf16_f32 v2, v2, v147
	ds_write_b16 v74, v2 offset:2784
	v_mul_f32_e32 v2, v40, v81
	v_cvt_pk_bf16_f32 v2, v2, v147
	ds_write_b16 v74, v2 offset:2848
	v_mul_f32_e32 v2, v24, v81
	v_cvt_pk_bf16_f32 v2, v2, v147
	ds_write_b16 v74, v2 offset:2912
	v_mul_f32_e32 v2, v9, v82
	v_cvt_pk_bf16_f32 v2, v2, v147
	ds_write_b16 v74, v2 offset:2992
	v_mul_f32_e32 v2, v57, v82
	v_cvt_pk_bf16_f32 v2, v2, v147
	v_rcp_f32_e32 v66, v66
	ds_write_b16 v74, v2 offset:3056
	v_mul_f32_e32 v2, v41, v82
	v_cvt_pk_bf16_f32 v2, v2, v147
	ds_write_b16 v74, v2 offset:3120
	v_mul_f32_e32 v2, v25, v82
	v_cvt_pk_bf16_f32 v2, v2, v147
	ds_write_b16 v74, v2 offset:3184
	v_mul_f32_e32 v2, v10, v66
	v_cvt_pk_bf16_f32 v2, v2, v147
	ds_write_b16 v74, v2 offset:4352
	v_mul_f32_e32 v2, v58, v66
	v_cvt_pk_bf16_f32 v2, v2, v147
	v_rcp_f32_e32 v67, v67
	ds_write_b16 v74, v2 offset:4416
	v_mul_f32_e32 v2, v42, v66
	v_cvt_pk_bf16_f32 v2, v2, v147
	ds_write_b16 v74, v2 offset:4480
	v_mul_f32_e32 v2, v26, v66
	v_cvt_pk_bf16_f32 v2, v2, v147
	ds_write_b16 v74, v2 offset:4544
	v_mul_f32_e32 v2, v11, v67
	v_cvt_pk_bf16_f32 v2, v2, v147
	ds_write_b16 v74, v2 offset:4624
	v_mul_f32_e32 v2, v59, v67
	v_cvt_pk_bf16_f32 v2, v2, v147
	v_rcp_f32_e32 v68, v68
	ds_write_b16 v74, v2 offset:4688
	v_mul_f32_e32 v2, v43, v67
	v_cvt_pk_bf16_f32 v2, v2, v147
	ds_write_b16 v74, v2 offset:4752
	v_mul_f32_e32 v2, v27, v67
	v_cvt_pk_bf16_f32 v2, v2, v147
	ds_write_b16 v74, v2 offset:4816
	v_mul_f32_e32 v2, v12, v68
	v_cvt_pk_bf16_f32 v2, v2, v147
	ds_write_b16 v74, v2 offset:4896
	v_mul_f32_e32 v2, v60, v68
	v_cvt_pk_bf16_f32 v2, v2, v147
	v_rcp_f32_e32 v69, v69
	ds_write_b16 v74, v2 offset:4960
	v_mul_f32_e32 v2, v44, v68
	v_cvt_pk_bf16_f32 v2, v2, v147
	ds_write_b16 v74, v2 offset:5024
	v_mul_f32_e32 v2, v28, v68
	v_cvt_pk_bf16_f32 v2, v2, v147
	ds_write_b16 v74, v2 offset:5088
	v_mul_f32_e32 v2, v13, v69
	v_cvt_pk_bf16_f32 v2, v2, v147
	ds_write_b16 v74, v2 offset:5168
	v_mul_f32_e32 v2, v61, v69
	v_cvt_pk_bf16_f32 v2, v2, v147
	v_rcp_f32_e32 v70, v70
	ds_write_b16 v74, v2 offset:5232
	v_mul_f32_e32 v2, v45, v69
	v_cvt_pk_bf16_f32 v2, v2, v147
	ds_write_b16 v74, v2 offset:5296
	v_mul_f32_e32 v2, v29, v69
	v_cvt_pk_bf16_f32 v2, v2, v147
	ds_write_b16 v74, v2 offset:5360
	v_mul_f32_e32 v2, v14, v70
	v_cvt_pk_bf16_f32 v2, v2, v147
	ds_write_b16 v74, v2 offset:6528
	v_mul_f32_e32 v2, v62, v70
	v_cvt_pk_bf16_f32 v2, v2, v147
	v_rcp_f32_e32 v71, v71
	ds_write_b16 v74, v2 offset:6592
	v_mul_f32_e32 v2, v46, v70
	v_cvt_pk_bf16_f32 v2, v2, v147
	ds_write_b16 v74, v2 offset:6656
	v_mul_f32_e32 v2, v30, v70
	v_cvt_pk_bf16_f32 v2, v2, v147
	ds_write_b16 v74, v2 offset:6720
	v_mul_f32_e32 v2, v15, v71
	v_cvt_pk_bf16_f32 v2, v2, v147
	ds_write_b16 v74, v2 offset:6800
	v_mul_f32_e32 v2, v63, v71
	v_cvt_pk_bf16_f32 v2, v2, v147
	v_rcp_f32_e32 v72, v72
	ds_write_b16 v74, v2 offset:6864
	v_mul_f32_e32 v2, v47, v71
	v_cvt_pk_bf16_f32 v2, v2, v147
	ds_write_b16 v74, v2 offset:6928
	v_mul_f32_e32 v2, v31, v71
	v_cvt_pk_bf16_f32 v2, v2, v147
	ds_write_b16 v74, v2 offset:6992
	v_mul_f32_e32 v2, v16, v72
	v_cvt_pk_bf16_f32 v2, v2, v147
	ds_write_b16 v74, v2 offset:7072
	v_mul_f32_e32 v2, v64, v72
	v_cvt_pk_bf16_f32 v2, v2, v147
	v_rcp_f32_e32 v73, v73
	ds_write_b16 v74, v2 offset:7136
	v_mul_f32_e32 v2, v48, v72
	v_cvt_pk_bf16_f32 v2, v2, v147
	ds_write_b16 v74, v2 offset:7200
	v_mul_f32_e32 v2, v32, v72
	v_cvt_pk_bf16_f32 v2, v2, v147
	ds_write_b16 v74, v2 offset:7264
	v_mul_f32_e32 v2, v17, v73
	v_cvt_pk_bf16_f32 v2, v2, v147
	ds_write_b16 v74, v2 offset:7344
	v_mul_f32_e32 v2, v65, v73
	v_cvt_pk_bf16_f32 v2, v2, v147
	ds_write_b16 v74, v2 offset:7408
	v_mul_f32_e32 v2, v49, v73
	v_cvt_pk_bf16_f32 v2, v2, v147
	ds_write_b16 v74, v2 offset:7472
	v_mul_f32_e32 v2, v33, v73
	v_cvt_pk_bf16_f32 v2, v2, v147
	ds_write_b16 v74, v2 offset:7536
	s_waitcnt lgkmcnt(0)
	s_add_i32 s53, s53, 1
	v_ashrrev_i32_e32 v16, 4, v149
	v_add_u32_e32 v2, s65, v16
	v_ashrrev_i32_e32 v3, 31, v2
	v_lshlrev_b64 v[2:3], 13, v[2:3]
	v_lshlrev_b32_e32 v4, 4, v149
	v_and_b32_e32 v146, 0xf0, v4
	v_lshl_add_u64 v[4:5], s[6:7], 0, v[2:3]
	v_lshl_add_u64 v[36:37], v[4:5], 0, v[146:147]
	global_load_dwordx4 v[4:7], v[36:37], off nt
	v_add_co_u32_e32 v8, vcc, s59, v36
	v_mul_lo_u32 v16, v16, s60
	s_nop 0
	v_addc_co_u32_e32 v9, vcc, 0, v37, vcc
	global_load_dwordx4 v[8:11], v[8:9], off nt
	v_add_co_u32_e32 v12, vcc, s56, v36
	v_add3_u32 v38, s28, v146, v16
	s_nop 0
	v_addc_co_u32_e32 v13, vcc, 0, v37, vcc
	global_load_dwordx4 v[12:15], v[12:13], off nt
	v_add_co_u32_e32 v20, vcc, s58, v36
	ds_read_b128 v[16:19], v38
	s_nop 0
	v_addc_co_u32_e32 v21, vcc, 0, v37, vcc
	global_load_dwordx4 v[20:23], v[20:21], off nt
	ds_read_b128 v[24:27], v38 offset:1088
	ds_read_b128 v[28:31], v38 offset:2176
	ds_read_b128 v[32:35], v38 offset:3264
	s_waitcnt lgkmcnt(3)
	v_lshlrev_b32_e32 v39, 16, v16
	v_and_b32_e32 v16, 0xffff0000, v16
	v_lshl_add_u64 v[2:3], s[4:5], 0, v[2:3]
	v_lshl_add_u64 v[2:3], v[2:3], 0, v[146:147]
	s_cmp_eq_u32 s53, 5
	s_cselect_b64 s[4:5], -1, 0
	s_waitcnt vmcnt(3)
	v_lshlrev_b32_e32 v40, 16, v4
	v_and_b32_e32 v4, 0xffff0000, v4
	v_mul_f32_e32 v39, v39, v40
	v_mul_f32_e32 v4, v16, v4
	v_cvt_pk_bf16_f32 v4, v39, v4
	v_lshlrev_b32_e32 v16, 16, v17
	v_lshlrev_b32_e32 v39, 16, v5
	v_and_b32_e32 v17, 0xffff0000, v17
	v_and_b32_e32 v5, 0xffff0000, v5
	v_mul_f32_e32 v16, v16, v39
	v_mul_f32_e32 v5, v17, v5
	v_cvt_pk_bf16_f32 v5, v16, v5
	v_lshlrev_b32_e32 v16, 16, v18
	v_lshlrev_b32_e32 v17, 16, v6
	v_mul_f32_e32 v16, v16, v17
	v_and_b32_e32 v17, 0xffff0000, v18
	v_and_b32_e32 v6, 0xffff0000, v6
	v_mul_f32_e32 v6, v17, v6
	v_cvt_pk_bf16_f32 v6, v16, v6
	v_lshlrev_b32_e32 v16, 16, v19
	v_lshlrev_b32_e32 v17, 16, v7
	v_mul_f32_e32 v16, v16, v17
	v_and_b32_e32 v17, 0xffff0000, v19
	v_and_b32_e32 v7, 0xffff0000, v7
	v_mul_f32_e32 v7, v17, v7
	v_cvt_pk_bf16_f32 v7, v16, v7
	global_store_dwordx4 v[2:3], v[4:7], off
	s_waitcnt vmcnt(3)
	s_nop 0
	v_lshlrev_b32_e32 v4, 16, v8
	s_waitcnt lgkmcnt(2)
	v_lshlrev_b32_e32 v5, 16, v24
	v_mul_f32_e32 v4, v5, v4
	v_and_b32_e32 v5, 0xffff0000, v24
	v_and_b32_e32 v6, 0xffff0000, v8
	v_mul_f32_e32 v5, v5, v6
	v_cvt_pk_bf16_f32 v4, v4, v5
	v_lshlrev_b32_e32 v5, 16, v9
	v_lshlrev_b32_e32 v6, 16, v25
	v_mul_f32_e32 v5, v6, v5
	v_and_b32_e32 v6, 0xffff0000, v25
	v_and_b32_e32 v7, 0xffff0000, v9
	v_mul_f32_e32 v6, v6, v7
	v_cvt_pk_bf16_f32 v5, v5, v6
	v_lshlrev_b32_e32 v6, 16, v10
	v_lshlrev_b32_e32 v7, 16, v26
	v_mul_f32_e32 v6, v7, v6
	v_and_b32_e32 v7, 0xffff0000, v26
	v_and_b32_e32 v8, 0xffff0000, v10
	v_mul_f32_e32 v7, v7, v8
	v_cvt_pk_bf16_f32 v6, v6, v7
	v_lshlrev_b32_e32 v7, 16, v11
	v_lshlrev_b32_e32 v8, 16, v27
	v_mul_f32_e32 v7, v8, v7
	v_and_b32_e32 v8, 0xffff0000, v27
	v_and_b32_e32 v9, 0xffff0000, v11
	v_mul_f32_e32 v8, v8, v9
	v_cvt_pk_bf16_f32 v7, v7, v8
	v_add_co_u32_e32 v8, vcc, s59, v2
	s_nop 1
	v_addc_co_u32_e32 v9, vcc, 0, v3, vcc
	global_store_dwordx4 v[8:9], v[4:7], off
	s_waitcnt vmcnt(3)
	v_and_b32_e32 v8, 0xffff0000, v14
	v_and_b32_e32 v9, 0xffff0000, v15
	v_lshlrev_b32_e32 v4, 16, v12
	s_waitcnt lgkmcnt(1)
	v_lshlrev_b32_e32 v5, 16, v28
	v_mul_f32_e32 v4, v5, v4
	v_and_b32_e32 v5, 0xffff0000, v28
	v_and_b32_e32 v6, 0xffff0000, v12
	v_mul_f32_e32 v5, v5, v6
	v_cvt_pk_bf16_f32 v4, v4, v5
	v_lshlrev_b32_e32 v5, 16, v13
	v_lshlrev_b32_e32 v6, 16, v29
	v_mul_f32_e32 v5, v6, v5
	v_and_b32_e32 v6, 0xffff0000, v29
	v_and_b32_e32 v7, 0xffff0000, v13
	v_mul_f32_e32 v6, v6, v7
	v_cvt_pk_bf16_f32 v5, v5, v6
	v_lshlrev_b32_e32 v6, 16, v14
	v_lshlrev_b32_e32 v7, 16, v30
	v_mul_f32_e32 v6, v7, v6
	v_and_b32_e32 v7, 0xffff0000, v30
	v_mul_f32_e32 v7, v7, v8
	v_cvt_pk_bf16_f32 v6, v6, v7
	v_lshlrev_b32_e32 v7, 16, v15
	v_lshlrev_b32_e32 v8, 16, v31
	v_mul_f32_e32 v7, v8, v7
	v_and_b32_e32 v8, 0xffff0000, v31
	v_mul_f32_e32 v8, v8, v9
	v_cvt_pk_bf16_f32 v7, v7, v8
	v_add_co_u32_e32 v8, vcc, s56, v2
	s_nop 1
	v_addc_co_u32_e32 v9, vcc, 0, v3, vcc
	global_store_dwordx4 v[8:9], v[4:7], off
	s_waitcnt vmcnt(3)
	v_and_b32_e32 v8, 0xffff0000, v22
	v_and_b32_e32 v9, 0xffff0000, v23
	v_lshlrev_b32_e32 v4, 16, v20
	s_waitcnt lgkmcnt(0)
	v_lshlrev_b32_e32 v5, 16, v32
	v_mul_f32_e32 v4, v5, v4
	v_and_b32_e32 v5, 0xffff0000, v32
	v_and_b32_e32 v6, 0xffff0000, v20
	v_mul_f32_e32 v5, v5, v6
	v_cvt_pk_bf16_f32 v4, v4, v5
	v_lshlrev_b32_e32 v5, 16, v21
	v_lshlrev_b32_e32 v6, 16, v33
	v_mul_f32_e32 v5, v6, v5
	v_and_b32_e32 v6, 0xffff0000, v33
	v_and_b32_e32 v7, 0xffff0000, v21
	v_mul_f32_e32 v6, v6, v7
	v_cvt_pk_bf16_f32 v5, v5, v6
	v_lshlrev_b32_e32 v6, 16, v22
	v_lshlrev_b32_e32 v7, 16, v34
	v_mul_f32_e32 v6, v7, v6
	v_and_b32_e32 v7, 0xffff0000, v34
	v_mul_f32_e32 v7, v7, v8
	v_cvt_pk_bf16_f32 v6, v6, v7
	v_lshlrev_b32_e32 v7, 16, v23
	v_lshlrev_b32_e32 v8, 16, v35
	v_mul_f32_e32 v7, v8, v7
	v_and_b32_e32 v8, 0xffff0000, v35
	v_mul_f32_e32 v8, v8, v9
	v_cvt_pk_bf16_f32 v7, v7, v8
	v_add_co_u32_e32 v8, vcc, s58, v2
	s_nop 1
	v_addc_co_u32_e32 v9, vcc, 0, v3, vcc
	global_store_dwordx4 v[8:9], v[4:7], off
	s_nop 1
	v_add_co_u32_e32 v4, vcc, s61, v36
	s_nop 1
	v_addc_co_u32_e32 v5, vcc, 0, v37, vcc
	global_load_dwordx4 v[4:7], v[4:5], off nt
	v_add_co_u32_e32 v8, vcc, s62, v36
	s_nop 1
	v_addc_co_u32_e32 v9, vcc, 0, v37, vcc
	global_load_dwordx4 v[8:11], v[8:9], off nt
	v_add_co_u32_e32 v12, vcc, s63, v36
	s_nop 1
	v_addc_co_u32_e32 v13, vcc, 0, v37, vcc
	global_load_dwordx4 v[12:15], v[12:13], off nt
	v_add_co_u32_e32 v16, vcc, s64, v36
	s_waitcnt vmcnt(2)
	v_lshlrev_b32_e32 v36, 16, v4
	v_addc_co_u32_e32 v17, vcc, 0, v37, vcc
	global_load_dwordx4 v[16:19], v[16:17], off nt
	ds_read_b128 v[20:23], v38 offset:4352
	ds_read_b128 v[24:27], v38 offset:5440
	ds_read_b128 v[28:31], v38 offset:6528
	ds_read_b128 v[32:35], v38 offset:7616
	v_and_b32_e32 v4, 0xffff0000, v4
	s_waitcnt lgkmcnt(3)
	v_lshlrev_b32_e32 v37, 16, v20
	v_and_b32_e32 v20, 0xffff0000, v20
	v_mul_f32_e32 v36, v37, v36
	v_mul_f32_e32 v4, v20, v4
	v_cvt_pk_bf16_f32 v4, v36, v4
	v_lshlrev_b32_e32 v20, 16, v5
	v_lshlrev_b32_e32 v36, 16, v21
	v_and_b32_e32 v21, 0xffff0000, v21
	v_and_b32_e32 v5, 0xffff0000, v5
	v_mul_f32_e32 v20, v36, v20
	v_mul_f32_e32 v5, v21, v5
	v_cvt_pk_bf16_f32 v5, v20, v5
	v_lshlrev_b32_e32 v20, 16, v6
	v_lshlrev_b32_e32 v21, 16, v22
	v_mul_f32_e32 v20, v21, v20
	v_and_b32_e32 v21, 0xffff0000, v22
	v_and_b32_e32 v6, 0xffff0000, v6
	v_mul_f32_e32 v6, v21, v6
	v_cvt_pk_bf16_f32 v6, v20, v6
	v_lshlrev_b32_e32 v20, 16, v7
	v_lshlrev_b32_e32 v21, 16, v23
	v_mul_f32_e32 v20, v21, v20
	v_and_b32_e32 v21, 0xffff0000, v23
	v_and_b32_e32 v7, 0xffff0000, v7
	v_mul_f32_e32 v7, v21, v7
	v_cvt_pk_bf16_f32 v7, v20, v7
	v_add_co_u32_e32 v20, vcc, s61, v2
	s_nop 1
	v_addc_co_u32_e32 v21, vcc, 0, v3, vcc
	global_store_dwordx4 v[20:21], v[4:7], off
	s_waitcnt vmcnt(3)
	s_nop 0
	v_lshlrev_b32_e32 v4, 16, v8
	s_waitcnt lgkmcnt(2)
	v_lshlrev_b32_e32 v5, 16, v24
	v_mul_f32_e32 v4, v5, v4
	v_and_b32_e32 v5, 0xffff0000, v24
	v_and_b32_e32 v6, 0xffff0000, v8
	v_mul_f32_e32 v5, v5, v6
	v_cvt_pk_bf16_f32 v4, v4, v5
	v_lshlrev_b32_e32 v5, 16, v9
	v_lshlrev_b32_e32 v6, 16, v25
	v_mul_f32_e32 v5, v6, v5
	v_and_b32_e32 v6, 0xffff0000, v25
	v_and_b32_e32 v7, 0xffff0000, v9
	v_mul_f32_e32 v6, v6, v7
	v_cvt_pk_bf16_f32 v5, v5, v6
	v_lshlrev_b32_e32 v6, 16, v10
	v_lshlrev_b32_e32 v7, 16, v26
	v_mul_f32_e32 v6, v7, v6
	v_and_b32_e32 v7, 0xffff0000, v26
	v_and_b32_e32 v8, 0xffff0000, v10
	v_mul_f32_e32 v7, v7, v8
	v_cvt_pk_bf16_f32 v6, v6, v7
	v_lshlrev_b32_e32 v7, 16, v11
	v_lshlrev_b32_e32 v8, 16, v27
	v_mul_f32_e32 v7, v8, v7
	v_and_b32_e32 v8, 0xffff0000, v27
	v_and_b32_e32 v9, 0xffff0000, v11
	v_mul_f32_e32 v8, v8, v9
	v_cvt_pk_bf16_f32 v7, v7, v8
	v_add_co_u32_e32 v8, vcc, s62, v2
	s_nop 1
	v_addc_co_u32_e32 v9, vcc, 0, v3, vcc
	global_store_dwordx4 v[8:9], v[4:7], off
	s_waitcnt vmcnt(3)
	v_and_b32_e32 v8, 0xffff0000, v14
	v_and_b32_e32 v9, 0xffff0000, v15
	v_lshlrev_b32_e32 v4, 16, v12
	s_waitcnt lgkmcnt(1)
	v_lshlrev_b32_e32 v5, 16, v28
	v_mul_f32_e32 v4, v5, v4
	v_and_b32_e32 v5, 0xffff0000, v28
	v_and_b32_e32 v6, 0xffff0000, v12
	v_mul_f32_e32 v5, v5, v6
	v_cvt_pk_bf16_f32 v4, v4, v5
	v_lshlrev_b32_e32 v5, 16, v13
	v_lshlrev_b32_e32 v6, 16, v29
	v_mul_f32_e32 v5, v6, v5
	v_and_b32_e32 v6, 0xffff0000, v29
	v_and_b32_e32 v7, 0xffff0000, v13
	v_mul_f32_e32 v6, v6, v7
	v_cvt_pk_bf16_f32 v5, v5, v6
	v_lshlrev_b32_e32 v6, 16, v14
	v_lshlrev_b32_e32 v7, 16, v30
	v_mul_f32_e32 v6, v7, v6
	v_and_b32_e32 v7, 0xffff0000, v30
	v_mul_f32_e32 v7, v7, v8
	v_cvt_pk_bf16_f32 v6, v6, v7
	v_lshlrev_b32_e32 v7, 16, v15
	v_lshlrev_b32_e32 v8, 16, v31
	v_mul_f32_e32 v7, v8, v7
	v_and_b32_e32 v8, 0xffff0000, v31
	v_mul_f32_e32 v8, v8, v9
	v_cvt_pk_bf16_f32 v7, v7, v8
	v_add_co_u32_e32 v8, vcc, s63, v2
	s_nop 1
	v_addc_co_u32_e32 v9, vcc, 0, v3, vcc
	global_store_dwordx4 v[8:9], v[4:7], off
	s_waitcnt vmcnt(3)
	v_and_b32_e32 v8, 0xffff0000, v18
	v_add_co_u32_e32 v2, vcc, s64, v2
	v_lshlrev_b32_e32 v4, 16, v16
	s_waitcnt lgkmcnt(0)
	v_lshlrev_b32_e32 v5, 16, v32
	v_mul_f32_e32 v4, v5, v4
	v_and_b32_e32 v5, 0xffff0000, v32
	v_and_b32_e32 v6, 0xffff0000, v16
	v_mul_f32_e32 v5, v5, v6
	v_cvt_pk_bf16_f32 v4, v4, v5
	v_lshlrev_b32_e32 v5, 16, v17
	v_lshlrev_b32_e32 v6, 16, v33
	v_mul_f32_e32 v5, v6, v5
	v_and_b32_e32 v6, 0xffff0000, v33
	v_and_b32_e32 v7, 0xffff0000, v17
	v_mul_f32_e32 v6, v6, v7
	v_cvt_pk_bf16_f32 v5, v5, v6
	v_lshlrev_b32_e32 v6, 16, v18
	v_lshlrev_b32_e32 v7, 16, v34
	v_mul_f32_e32 v6, v7, v6
	v_and_b32_e32 v7, 0xffff0000, v34
	v_mul_f32_e32 v7, v7, v8
	v_cvt_pk_bf16_f32 v6, v6, v7
	v_lshlrev_b32_e32 v7, 16, v19
	v_lshlrev_b32_e32 v8, 16, v35
	v_mul_f32_e32 v7, v8, v7
	v_and_b32_e32 v8, 0xffff0000, v35
	v_and_b32_e32 v9, 0xffff0000, v19
	v_addc_co_u32_e32 v3, vcc, 0, v3, vcc
	v_mul_f32_e32 v8, v8, v9
	v_cvt_pk_bf16_f32 v7, v7, v8
	global_store_dwordx4 v[2:3], v[4:7], off
	s_barrier
	s_barrier

.LBB0_812:
	s_ashr_i32 s29, s28, 31
	s_mul_i32 s5, s28, 0x1800
	s_mul_hi_i32 s4, s28, 0x1800
	s_add_u32 s5, s47, s5
	s_addc_u32 s7, s48, s4
	s_lshl_b32 s69, s6, 7
	s_lshl_b32 s4, s6, 8
	s_add_u32 s4, s5, s4
	s_addc_u32 s5, s7, 0
	s_mul_i32 s34, s30, 0x1800
	s_mul_hi_i32 s7, s30, 0x1800
	s_add_u32 s30, s47, s34
	s_addc_u32 s31, s48, s7
	s_lshl_b32 s6, s6, 6
	s_and_b32 s35, s6, 0x300
	s_waitcnt vmcnt(0)
	v_mov_b32_e32 v40, v0
	s_add_u32 s30, s30, s35
	s_addc_u32 s31, s31, 0
	v_readfirstlane_b32 s6, v40
	s_ashr_i32 s68, s6, 6
	v_and_b32_e32 v154, 31, v40
	s_lshl_b32 s65, s68, 5
	v_bfe_u32 v155, v40, 5, 1
	v_or_b32_e32 v4, s65, v154
	v_mov_b64_e32 v[2:3], s[4:5]
	v_mad_i64_i32 v[2:3], s[4:5], v4, s54, v[2:3]
	v_lshlrev_b32_e32 v148, 4, v155
	v_mov_b32_e32 v149, v147
	v_lshl_add_u64 v[2:3], v[2:3], 0, v[148:149]
	global_load_dwordx4 v[126:129], v[2:3], off nt
	global_load_dwordx4 v[122:125], v[2:3], off offset:32 nt
	global_load_dwordx4 v[118:121], v[2:3], off offset:64 nt
	global_load_dwordx4 v[114:117], v[2:3], off offset:96 nt
	global_load_dwordx4 v[110:113], v[2:3], off offset:128 nt
	global_load_dwordx4 v[106:109], v[2:3], off offset:160 nt
	global_load_dwordx4 v[102:105], v[2:3], off offset:192 nt
	global_load_dwordx4 v[98:101], v[2:3], off offset:224 nt
	s_lshl_b32 s74, s68, 10
	s_cmp_lg_u32 0, -1
	s_cselect_b32 s4, 0, 0
	s_add_i32 s74, s74, s4
	s_lshl_b32 s4, s68, 2
	v_bfe_u32 v35, v40, 4, 2
	v_bitop3_b32 v3, s4, v40, v35 bitop3:0x36
	v_or_b32_e32 v2, s4, v35
	v_lshlrev_b32_e32 v3, 4, v3
	s_ashr_i32 s5, s6, 4
	v_mul_lo_u32 v2, v2, s54
	v_and_b32_e32 v39, 0xf0, v3
	s_and_b32 s38, s5, -16
	v_bfe_u32 v36, v40, 2, 2
	v_lshrrev_b32_e32 v3, 1, v40
	s_lshr_b32 s5, s5, 1
	v_or_b32_e32 v146, v39, v2
	s_lshl_b32 s4, s68, 1
	v_or_b32_e32 v2, s38, v36
	v_and_b32_e32 v37, 8, v3
	s_and_b32 s39, s5, 4
	v_lshlrev_b32_e32 v34, 4, v40
	v_or3_b32 v2, v2, v37, s39
	v_and_or_b32 v3, s4, 2, v155
	v_lshlrev_b32_e32 v3, 6, v3
	v_and_b32_e32 v38, 48, v34
	v_mul_lo_u32 v2, v2, s54
	s_add_i32 s76, s74, 0xc000
	v_or3_b32 v6, v3, v38, v2
	v_lshl_add_u64 v[2:3], s[30:31], 0, v[146:147]
	s_mov_b64 s[4:5], 0x1000
	v_lshl_add_u64 v[4:5], v[2:3], 0, s[4:5]
	s_mov_b32 m0, s76
	s_mov_b64 s[4:5], 0x31000
	global_load_lds_dwordx4 v[4:5], off
	v_lshl_add_u64 v[4:5], v[2:3], 0, s[4:5]
	s_add_i32 m0, s74, 0xe000
	v_mov_b32_e32 v146, v6
	global_load_lds_dwordx4 v[4:5], off
	v_lshl_add_u64 v[4:5], s[30:31], 0, v[146:147]
	s_mov_b64 s[4:5], 0x1400
	v_lshl_add_u64 v[6:7], v[4:5], 0, s[4:5]
	s_mov_b32 m0, s74
	s_mov_b64 s[4:5], 0x31400
	global_load_lds_dwordx4 v[6:7], off
	v_lshl_add_u64 v[6:7], v[4:5], 0, s[4:5]
	s_add_i32 m0, s74, 0x2000
	s_mov_b64 s[4:5], 0x61000
	global_load_lds_dwordx4 v[6:7], off
	s_add_i32 m0, s74, 0x10000
	v_lshl_add_u64 v[6:7], v[2:3], 0, s[4:5]
	s_mov_b64 s[4:5], 0x91000
	global_load_lds_dwordx4 v[6:7], off
	v_lshl_add_u64 v[6:7], v[2:3], 0, s[4:5]
	s_add_i32 m0, s74, 0x12000
	s_mov_b64 s[4:5], 0x61400
	global_load_lds_dwordx4 v[6:7], off
	s_add_i32 m0, s74, 0x4000
	v_lshl_add_u64 v[6:7], v[4:5], 0, s[4:5]
	s_mov_b64 s[4:5], 0x91400
	global_load_lds_dwordx4 v[6:7], off
	v_lshl_add_u64 v[4:5], v[4:5], 0, s[4:5]
	s_add_i32 m0, s74, 0x6000
	s_mov_b64 s[4:5], 0xc1000
	v_lshlrev_b32_e32 v158, 8, v154
	global_load_lds_dwordx4 v[4:5], off
	s_add_i32 m0, s74, 0x14000
	v_lshl_add_u64 v[4:5], v[2:3], 0, s[4:5]
	s_mov_b64 s[4:5], 0xf1000
	global_load_lds_dwordx4 v[4:5], off
	v_lshl_add_u64 v[2:3], v[2:3], 0, s[4:5]
	s_add_i32 m0, s74, 0x16000
	v_and_b32_e32 v56, 0xf0, v34
	v_add_u32_e32 v57, 0, v158
	global_load_lds_dwordx4 v[2:3], off
	v_xad_u32 v6, v148, v56, v57
	s_waitcnt vmcnt(0)
	s_waitcnt vmcnt(0) lgkmcnt(0)
	s_barrier
	ds_read_b128 v[2:5], v6 offset:49152
	ds_read_b128 v[6:9], v6 offset:57344
	s_waitcnt lgkmcnt(1)
	v_mfma_f32_32x32x16_bf16 v[18:33], v[2:5], v[126:129], 0
	v_or_b32_e32 v41, 32, v148
	v_xad_u32 v46, v41, v56, v57
	ds_read_b128 v[42:45], v46 offset:49152
	ds_read_b128 v[46:49], v46 offset:57344
	s_waitcnt lgkmcnt(2)
	v_mfma_f32_32x32x16_bf16 v[2:17], v[6:9], v[126:129], 0
	s_waitcnt lgkmcnt(1)
	v_mfma_f32_32x32x16_bf16 v[18:33], v[42:45], v[122:125], v[18:33]
	v_or_b32_e32 v42, 64, v148
	v_xad_u32 v43, v42, v56, v57
	s_waitcnt lgkmcnt(0)
	v_mfma_f32_32x32x16_bf16 v[2:17], v[46:49], v[122:125], v[2:17]
	ds_read_b128 v[44:47], v43 offset:49152
	ds_read_b128 v[48:51], v43 offset:57344
	v_or_b32_e32 v43, 0x60, v148
	s_waitcnt lgkmcnt(1)
	v_mfma_f32_32x32x16_bf16 v[18:33], v[44:47], v[118:121], v[18:33]
	s_waitcnt lgkmcnt(0)
	v_mfma_f32_32x32x16_bf16 v[2:17], v[48:51], v[118:121], v[2:17]
	v_xad_u32 v48, v43, v56, v57
	ds_read_b128 v[44:47], v48 offset:49152
	ds_read_b128 v[48:51], v48 offset:57344
	s_waitcnt lgkmcnt(1)
	v_mfma_f32_32x32x16_bf16 v[18:33], v[44:47], v[114:117], v[18:33]
	v_or_b32_e32 v44, 0x80, v148
	v_xad_u32 v45, v44, v56, v57
	s_waitcnt lgkmcnt(0)
	v_mfma_f32_32x32x16_bf16 v[2:17], v[48:51], v[114:117], v[2:17]
	ds_read_b128 v[46:49], v45 offset:49152
	ds_read_b128 v[50:53], v45 offset:57344
	v_or_b32_e32 v45, 0xa0, v148
	s_waitcnt lgkmcnt(1)
	v_mfma_f32_32x32x16_bf16 v[18:33], v[46:49], v[110:113], v[18:33]
	s_waitcnt lgkmcnt(0)
	v_mfma_f32_32x32x16_bf16 v[2:17], v[50:53], v[110:113], v[2:17]
	v_xad_u32 v50, v45, v56, v57
	ds_read_b128 v[46:49], v50 offset:49152
	ds_read_b128 v[50:53], v50 offset:57344
	s_waitcnt lgkmcnt(1)
	v_mfma_f32_32x32x16_bf16 v[18:33], v[46:49], v[106:109], v[18:33]
	v_or_b32_e32 v46, 0xc0, v148
	v_xad_u32 v47, v46, v56, v57
	s_waitcnt lgkmcnt(0)
	v_mfma_f32_32x32x16_bf16 v[2:17], v[50:53], v[106:109], v[2:17]
	ds_read_b128 v[48:51], v47 offset:49152
	ds_read_b128 v[52:55], v47 offset:57344
	v_or_b32_e32 v47, 0xe0, v148
	s_waitcnt lgkmcnt(1)
	v_mfma_f32_32x32x16_bf16 v[18:33], v[48:51], v[102:105], v[18:33]
	s_waitcnt lgkmcnt(0)
	v_mfma_f32_32x32x16_bf16 v[2:17], v[52:55], v[102:105], v[2:17]
	v_xad_u32 v52, v47, v56, v57
	ds_read_b128 v[48:51], v52 offset:49152
	ds_read_b128 v[52:55], v52 offset:57344
	s_waitcnt lgkmcnt(1)
	v_mfma_f32_32x32x16_bf16 v[18:33], v[48:51], v[98:101], v[18:33]
	s_waitcnt lgkmcnt(0)
	v_mfma_f32_32x32x16_bf16 v[2:17], v[52:55], v[98:101], v[2:17]
	s_nop 9
	v_max_f32_e32 v48, v19, v19
	v_max_f32_e32 v49, v18, v18
	v_max_f32_e32 v48, v49, v48
	v_max3_f32 v48, v48, v20, v21
	v_max3_f32 v48, v48, v22, v23
	v_max3_f32 v48, v48, v24, v25
	v_max3_f32 v48, v48, v26, v27
	v_max3_f32 v48, v48, v28, v29
	v_max3_f32 v48, v48, v30, v31
	v_max3_f32 v48, v48, v32, v33
	v_max3_f32 v48, v48, v2, v3
	v_max3_f32 v48, v48, v4, v5
	v_max3_f32 v48, v48, v6, v7
	v_max3_f32 v48, v48, v8, v9
	v_max3_f32 v48, v48, v10, v11
	v_max3_f32 v48, v48, v12, v13
	v_max3_f32 v48, v48, v14, v15
	v_max3_f32 v48, v48, v16, v17
	v_mov_b32_e32 v49, v48
	s_nop 1
	v_permlane32_swap_b32_e32 v48, v49
	v_max_f32_e32 v49, v49, v49
	v_max_f32_e32 v48, v48, v48
	v_max_f32_e32 v48, v48, v49
	v_add_f32_e32 v49, 0x7149f2ca, v48
	v_cmp_ge_f32_e32 vcc, s57, v49
	s_cmp_eq_u64 vcc, exec
	v_max_f32_e32 v48, 0xf149f2ca, v48
	s_cselect_b64 s[4:5], -1, 0
	v_cndmask_b32_e64 v166, v48, v1, s[4:5]
	v_mul_f32_e32 v49, 0xbe0293ee, v166
	v_fmamk_f32 v18, v18, 0x3e0293ee, v49
	v_fmamk_f32 v19, v19, 0x3e0293ee, v49
	v_fmamk_f32 v20, v20, 0x3e0293ee, v49
	v_fmamk_f32 v21, v21, 0x3e0293ee, v49
	v_fmamk_f32 v22, v22, 0x3e0293ee, v49
	v_fmamk_f32 v23, v23, 0x3e0293ee, v49
	v_fmamk_f32 v24, v24, 0x3e0293ee, v49
	v_fmamk_f32 v25, v25, 0x3e0293ee, v49
	v_fmamk_f32 v26, v26, 0x3e0293ee, v49
	v_fmamk_f32 v27, v27, 0x3e0293ee, v49
	v_fmamk_f32 v28, v28, 0x3e0293ee, v49
	v_fmamk_f32 v29, v29, 0x3e0293ee, v49
	v_fmamk_f32 v30, v30, 0x3e0293ee, v49
	v_fmamk_f32 v31, v31, 0x3e0293ee, v49
	v_fmamk_f32 v32, v32, 0x3e0293ee, v49
	v_fmamk_f32 v33, v33, 0x3e0293ee, v49
	v_fmamk_f32 v2, v2, 0x3e0293ee, v49
	v_fmamk_f32 v3, v3, 0x3e0293ee, v49
	v_fmamk_f32 v4, v4, 0x3e0293ee, v49
	v_fmamk_f32 v5, v5, 0x3e0293ee, v49
	v_fmamk_f32 v6, v6, 0x3e0293ee, v49
	v_fmamk_f32 v7, v7, 0x3e0293ee, v49
	v_fmamk_f32 v8, v8, 0x3e0293ee, v49
	v_fmamk_f32 v9, v9, 0x3e0293ee, v49
	v_fmamk_f32 v10, v10, 0x3e0293ee, v49
	v_fmamk_f32 v11, v11, 0x3e0293ee, v49
	v_fmamk_f32 v12, v12, 0x3e0293ee, v49
	v_fmamk_f32 v13, v13, 0x3e0293ee, v49
	v_fmamk_f32 v14, v14, 0x3e0293ee, v49
	v_fmamk_f32 v15, v15, 0x3e0293ee, v49
	v_fmamk_f32 v16, v16, 0x3e0293ee, v49
	v_fmac_f32_e32 v49, 0x3e0293ee, v17
	v_exp_f32_e32 v17, v18
	v_exp_f32_e32 v18, v19
	v_exp_f32_e32 v19, v20
	v_exp_f32_e32 v20, v21
	v_exp_f32_e32 v21, v22
	v_exp_f32_e32 v22, v23
	v_exp_f32_e32 v23, v24
	v_exp_f32_e32 v24, v25
	v_exp_f32_e32 v25, v26
	v_exp_f32_e32 v26, v27
	v_exp_f32_e32 v27, v28
	v_exp_f32_e32 v28, v29
	v_exp_f32_e32 v29, v30
	v_exp_f32_e32 v30, v31
	v_exp_f32_e32 v31, v32
	v_exp_f32_e32 v32, v33
	v_exp_f32_e32 v33, v2
	v_add_f32_e32 v2, 0, v17
	v_add_f32_e32 v2, v18, v2
	v_add_f32_e32 v2, v19, v2
	v_add_f32_e32 v2, v20, v2
	v_add_f32_e32 v2, v21, v2
	v_add_f32_e32 v2, v22, v2
	v_add_f32_e32 v2, v23, v2
	v_add_f32_e32 v2, v24, v2
	v_add_f32_e32 v2, v25, v2
	v_add_f32_e32 v2, v26, v2
	v_add_f32_e32 v2, v27, v2
	v_add_f32_e32 v2, v28, v2
	v_add_f32_e32 v2, v29, v2
	v_exp_f32_e32 v50, v3
	v_add_f32_e32 v2, v30, v2
	v_exp_f32_e32 v4, v4
	v_add_f32_e32 v2, v31, v2
	v_exp_f32_e32 v5, v5
	v_add_f32_e32 v2, v32, v2
	v_exp_f32_e32 v6, v6
	v_add_f32_e32 v2, v33, v2
	v_exp_f32_e32 v7, v7
	v_add_f32_e32 v2, v50, v2
	v_exp_f32_e32 v8, v8
	v_add_f32_e32 v2, v4, v2
	v_exp_f32_e32 v9, v9
	v_add_f32_e32 v2, v5, v2
	v_exp_f32_e32 v10, v10
	v_add_f32_e32 v2, v6, v2
	v_exp_f32_e32 v11, v11
	v_add_f32_e32 v2, v7, v2
	v_exp_f32_e32 v12, v12
	v_add_f32_e32 v2, v8, v2
	v_exp_f32_e32 v13, v13
	v_add_f32_e32 v2, v9, v2
	v_exp_f32_e32 v14, v14
	v_add_f32_e32 v2, v10, v2
	v_exp_f32_e32 v15, v15
	v_add_f32_e32 v2, v11, v2
	v_exp_f32_e32 v16, v16
	v_add_f32_e32 v2, v12, v2
	v_exp_f32_e32 v49, v49
	v_add_f32_e32 v2, v13, v2
	v_add_f32_e32 v2, v14, v2
	v_add_f32_e32 v2, v15, v2
	v_add_f32_e32 v2, v16, v2
	v_add_f32_e32 v2, v49, v2
	s_cmpk_lt_u32 s6, 0x100
	v_mov_b32_e32 v3, v2
	v_cvt_pk_bf16_f32 v134, v17, v18
	v_cvt_pk_bf16_f32 v135, v19, v20
	v_cvt_pk_bf16_f32 v136, v21, v22
	v_cvt_pk_bf16_f32 v137, v23, v24
	v_cvt_pk_bf16_f32 v142, v25, v26
	v_cvt_pk_bf16_f32 v143, v27, v28
	v_cvt_pk_bf16_f32 v144, v29, v30
	v_cvt_pk_bf16_f32 v145, v31, v32
	v_cvt_pk_bf16_f32 v130, v33, v50
	v_cvt_pk_bf16_f32 v131, v4, v5
	v_cvt_pk_bf16_f32 v132, v6, v7
	v_cvt_pk_bf16_f32 v133, v8, v9
	v_cvt_pk_bf16_f32 v138, v10, v11
	v_cvt_pk_bf16_f32 v139, v12, v13
	v_cvt_pk_bf16_f32 v140, v14, v15
	v_cvt_pk_bf16_f32 v141, v16, v49
	s_cselect_b64 s[30:31], -1, 0
	s_nop 0
	v_permlane32_swap_b32_e32 v2, v3
	v_permlane32_swap_b32_e32 v134, v136
	v_permlane32_swap_b32_e32 v135, v137
	v_permlane32_swap_b32_e32 v142, v144
	v_permlane32_swap_b32_e32 v143, v145
	v_permlane32_swap_b32_e32 v130, v132
	v_permlane32_swap_b32_e32 v131, v133
	v_permlane32_swap_b32_e32 v138, v140
	v_permlane32_swap_b32_e32 v139, v141
	s_and_b64 vcc, exec, s[30:31]
	s_cbranch_vccnz .LBB0_814
	s_barrier

.LBB0_837:
	s_or_b64 exec, exec, s[6:7]
	s_waitcnt lgkmcnt(0)
	v_add_u32_e32 v74, s72, v166
	ds_read_b128 v[66:69], v74
	ds_read_b128 v[70:73], v74 offset:32
	s_lshl_b64 s[6:7], s[24:25], 13
	s_add_u32 s4, s42, s6
	s_addc_u32 s5, s43, s7
	s_lshl_b32 s24, s69, 8
	s_add_u32 s4, s4, s24
	s_addc_u32 s5, s5, 0
	s_waitcnt lgkmcnt(1)
	v_rcp_f32_e32 v75, v66
	s_add_u32 s6, s0, s6
	s_addc_u32 s7, s1, s7
	v_rcp_f32_e32 v76, v67
	v_rcp_f32_e32 v77, v68
	v_rcp_f32_e32 v78, v69
	s_waitcnt lgkmcnt(0)
	v_rcp_f32_e32 v79, v70
	ds_read_b128 v[66:69], v74 offset:64
	v_rcp_f32_e32 v80, v71
	v_rcp_f32_e32 v81, v72
	v_rcp_f32_e32 v82, v73
	ds_read_b128 v[70:73], v74 offset:96
	v_mul_u32_u24_e32 v74, 0x440, v182
	s_add_u32 s6, s6, s24
	s_mulk_i32 s70, 0x2200
	v_lshl_or_b32 v74, v163, 1, v74
	s_addc_u32 s7, s7, 0
	s_waitcnt lgkmcnt(0)
	s_barrier
	s_add_i32 s24, s70, 0
	v_mul_f32_e32 v2, v2, v75
	v_add_u32_e32 v74, s24, v74
	v_cvt_pk_bf16_f32 v2, v2, v165
	ds_write_b16 v74, v2
	v_mul_f32_e32 v2, v50, v75
	v_cvt_pk_bf16_f32 v2, v2, v165
	ds_write_b16 v74, v2 offset:64
	v_mul_f32_e32 v2, v34, v75
	v_cvt_pk_bf16_f32 v2, v2, v165
	ds_write_b16 v74, v2 offset:128
	v_mul_f32_e32 v2, v18, v75
	v_cvt_pk_bf16_f32 v2, v2, v165
	ds_write_b16 v74, v2 offset:192
	v_mul_f32_e32 v2, v3, v76
	v_cvt_pk_bf16_f32 v2, v2, v165
	ds_write_b16 v74, v2 offset:272
	v_mul_f32_e32 v2, v51, v76
	v_cvt_pk_bf16_f32 v2, v2, v165
	ds_write_b16 v74, v2 offset:336
	v_mul_f32_e32 v2, v35, v76
	v_cvt_pk_bf16_f32 v2, v2, v165
	ds_write_b16 v74, v2 offset:400
	v_mul_f32_e32 v2, v19, v76
	v_cvt_pk_bf16_f32 v2, v2, v165
	ds_write_b16 v74, v2 offset:464
	v_mul_f32_e32 v2, v4, v77
	v_cvt_pk_bf16_f32 v2, v2, v165
	ds_write_b16 v74, v2 offset:544
	v_mul_f32_e32 v2, v52, v77
	v_cvt_pk_bf16_f32 v2, v2, v165
	ds_write_b16 v74, v2 offset:608
	v_mul_f32_e32 v2, v36, v77
	v_cvt_pk_bf16_f32 v2, v2, v165
	ds_write_b16 v74, v2 offset:672
	v_mul_f32_e32 v2, v20, v77
	v_cvt_pk_bf16_f32 v2, v2, v165
	ds_write_b16 v74, v2 offset:736
	v_mul_f32_e32 v2, v5, v78
	v_cvt_pk_bf16_f32 v2, v2, v165
	ds_write_b16 v74, v2 offset:816
	v_mul_f32_e32 v2, v53, v78
	v_cvt_pk_bf16_f32 v2, v2, v165
	ds_write_b16 v74, v2 offset:880
	v_mul_f32_e32 v2, v37, v78
	v_cvt_pk_bf16_f32 v2, v2, v165
	ds_write_b16 v74, v2 offset:944
	v_mul_f32_e32 v2, v21, v78
	v_cvt_pk_bf16_f32 v2, v2, v165
	ds_write_b16 v74, v2 offset:1008
	v_mul_f32_e32 v2, v6, v79
	v_cvt_pk_bf16_f32 v2, v2, v165
	ds_write_b16 v74, v2 offset:2176
	v_mul_f32_e32 v2, v54, v79
	v_cvt_pk_bf16_f32 v2, v2, v165
	ds_write_b16 v74, v2 offset:2240
	v_mul_f32_e32 v2, v38, v79
	v_cvt_pk_bf16_f32 v2, v2, v165
	ds_write_b16 v74, v2 offset:2304
	v_mul_f32_e32 v2, v22, v79
	v_cvt_pk_bf16_f32 v2, v2, v165
	ds_write_b16 v74, v2 offset:2368
	v_mul_f32_e32 v2, v7, v80
	v_cvt_pk_bf16_f32 v2, v2, v165
	ds_write_b16 v74, v2 offset:2448
	v_mul_f32_e32 v2, v55, v80
	v_cvt_pk_bf16_f32 v2, v2, v165
	ds_write_b16 v74, v2 offset:2512
	v_mul_f32_e32 v2, v39, v80
	v_cvt_pk_bf16_f32 v2, v2, v165
	ds_write_b16 v74, v2 offset:2576
	v_mul_f32_e32 v2, v23, v80
	v_cvt_pk_bf16_f32 v2, v2, v165
	ds_write_b16 v74, v2 offset:2640
	v_mul_f32_e32 v2, v8, v81
	v_cvt_pk_bf16_f32 v2, v2, v165
	ds_write_b16 v74, v2 offset:2720
	v_mul_f32_e32 v2, v56, v81
	v_cvt_pk_bf16_f32 v2, v2, v165
	ds_write_b16 v74, v2 offset:2784
	v_mul_f32_e32 v2, v40, v81
	v_cvt_pk_bf16_f32 v2, v2, v165
	ds_write_b16 v74, v2 offset:2848
	v_mul_f32_e32 v2, v24, v81
	v_cvt_pk_bf16_f32 v2, v2, v165
	ds_write_b16 v74, v2 offset:2912
	v_mul_f32_e32 v2, v9, v82
	v_cvt_pk_bf16_f32 v2, v2, v165
	ds_write_b16 v74, v2 offset:2992
	v_mul_f32_e32 v2, v57, v82
	v_cvt_pk_bf16_f32 v2, v2, v165
	v_rcp_f32_e32 v66, v66
	ds_write_b16 v74, v2 offset:3056
	v_mul_f32_e32 v2, v41, v82
	v_cvt_pk_bf16_f32 v2, v2, v165
	ds_write_b16 v74, v2 offset:3120
	v_mul_f32_e32 v2, v25, v82
	v_cvt_pk_bf16_f32 v2, v2, v165
	ds_write_b16 v74, v2 offset:3184
	v_mul_f32_e32 v2, v10, v66
	v_cvt_pk_bf16_f32 v2, v2, v165
	ds_write_b16 v74, v2 offset:4352
	v_mul_f32_e32 v2, v58, v66
	v_cvt_pk_bf16_f32 v2, v2, v165
	v_rcp_f32_e32 v67, v67
	ds_write_b16 v74, v2 offset:4416
	v_mul_f32_e32 v2, v42, v66
	v_cvt_pk_bf16_f32 v2, v2, v165
	ds_write_b16 v74, v2 offset:4480
	v_mul_f32_e32 v2, v26, v66
	v_cvt_pk_bf16_f32 v2, v2, v165
	ds_write_b16 v74, v2 offset:4544
	v_mul_f32_e32 v2, v11, v67
	v_cvt_pk_bf16_f32 v2, v2, v165
	ds_write_b16 v74, v2 offset:4624
	v_mul_f32_e32 v2, v59, v67
	v_cvt_pk_bf16_f32 v2, v2, v165
	v_rcp_f32_e32 v68, v68
	ds_write_b16 v74, v2 offset:4688
	v_mul_f32_e32 v2, v43, v67
	v_cvt_pk_bf16_f32 v2, v2, v165
	ds_write_b16 v74, v2 offset:4752
	v_mul_f32_e32 v2, v27, v67
	v_cvt_pk_bf16_f32 v2, v2, v165
	ds_write_b16 v74, v2 offset:4816
	v_mul_f32_e32 v2, v12, v68
	v_cvt_pk_bf16_f32 v2, v2, v165
	ds_write_b16 v74, v2 offset:4896
	v_mul_f32_e32 v2, v60, v68
	v_cvt_pk_bf16_f32 v2, v2, v165
	v_rcp_f32_e32 v69, v69
	ds_write_b16 v74, v2 offset:4960
	v_mul_f32_e32 v2, v44, v68
	v_cvt_pk_bf16_f32 v2, v2, v165
	ds_write_b16 v74, v2 offset:5024
	v_mul_f32_e32 v2, v28, v68
	v_cvt_pk_bf16_f32 v2, v2, v165
	ds_write_b16 v74, v2 offset:5088
	v_mul_f32_e32 v2, v13, v69
	v_cvt_pk_bf16_f32 v2, v2, v165
	ds_write_b16 v74, v2 offset:5168
	v_mul_f32_e32 v2, v61, v69
	v_cvt_pk_bf16_f32 v2, v2, v165
	v_rcp_f32_e32 v70, v70
	ds_write_b16 v74, v2 offset:5232
	v_mul_f32_e32 v2, v45, v69
	v_cvt_pk_bf16_f32 v2, v2, v165
	ds_write_b16 v74, v2 offset:5296
	v_mul_f32_e32 v2, v29, v69
	v_cvt_pk_bf16_f32 v2, v2, v165
	ds_write_b16 v74, v2 offset:5360
	v_mul_f32_e32 v2, v14, v70
	v_cvt_pk_bf16_f32 v2, v2, v165
	ds_write_b16 v74, v2 offset:6528
	v_mul_f32_e32 v2, v62, v70
	v_cvt_pk_bf16_f32 v2, v2, v165
	v_rcp_f32_e32 v71, v71
	ds_write_b16 v74, v2 offset:6592
	v_mul_f32_e32 v2, v46, v70
	v_cvt_pk_bf16_f32 v2, v2, v165
	ds_write_b16 v74, v2 offset:6656
	v_mul_f32_e32 v2, v30, v70
	v_cvt_pk_bf16_f32 v2, v2, v165
	ds_write_b16 v74, v2 offset:6720
	v_mul_f32_e32 v2, v15, v71
	v_cvt_pk_bf16_f32 v2, v2, v165
	ds_write_b16 v74, v2 offset:6800
	v_mul_f32_e32 v2, v63, v71
	v_cvt_pk_bf16_f32 v2, v2, v165
	v_rcp_f32_e32 v72, v72
	ds_write_b16 v74, v2 offset:6864
	v_mul_f32_e32 v2, v47, v71
	v_cvt_pk_bf16_f32 v2, v2, v165
	ds_write_b16 v74, v2 offset:6928
	v_mul_f32_e32 v2, v31, v71
	v_cvt_pk_bf16_f32 v2, v2, v165
	ds_write_b16 v74, v2 offset:6992
	v_mul_f32_e32 v2, v16, v72
	v_cvt_pk_bf16_f32 v2, v2, v165
	ds_write_b16 v74, v2 offset:7072
	v_mul_f32_e32 v2, v64, v72
	v_cvt_pk_bf16_f32 v2, v2, v165
	v_rcp_f32_e32 v73, v73
	ds_write_b16 v74, v2 offset:7136
	v_mul_f32_e32 v2, v48, v72
	v_cvt_pk_bf16_f32 v2, v2, v165
	ds_write_b16 v74, v2 offset:7200
	v_mul_f32_e32 v2, v32, v72
	v_cvt_pk_bf16_f32 v2, v2, v165
	ds_write_b16 v74, v2 offset:7264
	v_mul_f32_e32 v2, v17, v73
	v_cvt_pk_bf16_f32 v2, v2, v165
	ds_write_b16 v74, v2 offset:7344
	v_mul_f32_e32 v2, v65, v73
	v_cvt_pk_bf16_f32 v2, v2, v165
	ds_write_b16 v74, v2 offset:7408
	v_mul_f32_e32 v2, v49, v73
	v_cvt_pk_bf16_f32 v2, v2, v165
	ds_write_b16 v74, v2 offset:7472
	v_mul_f32_e32 v2, v33, v73
	v_cvt_pk_bf16_f32 v2, v2, v165
	ds_write_b16 v74, v2 offset:7536
	s_waitcnt lgkmcnt(0)
	s_add_i32 s34, s34, 1
	v_ashrrev_i32_e32 v20, 4, v167
	v_add_u32_e32 v2, s68, v20
	v_ashrrev_i32_e32 v3, 31, v2
	v_lshlrev_b64 v[2:3], 13, v[2:3]
	v_lshlrev_b32_e32 v4, 4, v167
	v_and_b32_e32 v164, 0xf0, v4
	v_lshl_add_u64 v[4:5], s[6:7], 0, v[2:3]
	v_lshl_add_u64 v[36:37], v[4:5], 0, v[164:165]
	v_add_co_u32_e32 v4, vcc, s57, v36
	v_mul_lo_u32 v20, v20, s61
	s_nop 0
	v_addc_co_u32_e32 v5, vcc, 0, v37, vcc
	global_load_dwordx4 v[4:7], v[4:5], off nt
	v_add_co_u32_e32 v8, vcc, s58, v36
	v_add3_u32 v38, s24, v164, v20
	s_nop 0
	v_addc_co_u32_e32 v9, vcc, 0, v37, vcc
	global_load_dwordx4 v[8:11], v[8:9], off nt
	v_add_co_u32_e32 v12, vcc, s59, v36
	v_lshl_add_u64 v[2:3], s[4:5], 0, v[2:3]
	s_nop 0
	v_addc_co_u32_e32 v13, vcc, 0, v37, vcc
	global_load_dwordx4 v[12:15], v[12:13], off nt
	v_add_co_u32_e32 v16, vcc, s60, v36
	v_lshl_add_u64 v[2:3], v[2:3], 0, v[164:165]
	s_nop 0
	v_addc_co_u32_e32 v17, vcc, 0, v37, vcc
	global_load_dwordx4 v[16:19], v[16:17], off nt
	ds_read_b128 v[20:23], v38
	ds_read_b128 v[24:27], v38 offset:1088
	ds_read_b128 v[28:31], v38 offset:2176
	ds_read_b128 v[32:35], v38 offset:3264
	s_cmp_eq_u32 s34, 5
	s_waitcnt lgkmcnt(3)
	v_lshlrev_b32_e32 v40, 16, v20
	v_and_b32_e32 v20, 0xffff0000, v20
	s_cselect_b64 s[4:5], -1, 0
	s_waitcnt vmcnt(3)
	v_lshlrev_b32_e32 v39, 16, v4
	v_and_b32_e32 v4, 0xffff0000, v4
	v_mul_f32_e32 v39, v40, v39
	v_mul_f32_e32 v4, v20, v4
	v_cvt_pk_bf16_f32 v4, v39, v4
	v_lshlrev_b32_e32 v20, 16, v5
	v_lshlrev_b32_e32 v39, 16, v21
	v_and_b32_e32 v21, 0xffff0000, v21
	v_and_b32_e32 v5, 0xffff0000, v5
	v_mul_f32_e32 v20, v39, v20
	v_mul_f32_e32 v5, v21, v5
	v_cvt_pk_bf16_f32 v5, v20, v5
	v_lshlrev_b32_e32 v20, 16, v6
	v_lshlrev_b32_e32 v21, 16, v22
	v_mul_f32_e32 v20, v21, v20
	v_and_b32_e32 v21, 0xffff0000, v22
	v_and_b32_e32 v6, 0xffff0000, v6
	v_mul_f32_e32 v6, v21, v6
	v_cvt_pk_bf16_f32 v6, v20, v6
	v_lshlrev_b32_e32 v20, 16, v7
	v_lshlrev_b32_e32 v21, 16, v23
	v_mul_f32_e32 v20, v21, v20
	v_and_b32_e32 v21, 0xffff0000, v23
	v_and_b32_e32 v7, 0xffff0000, v7
	v_mul_f32_e32 v7, v21, v7
	v_cvt_pk_bf16_f32 v7, v20, v7
	v_add_co_u32_e32 v20, vcc, s57, v2
	s_nop 1
	v_addc_co_u32_e32 v21, vcc, 0, v3, vcc
	global_store_dwordx4 v[20:21], v[4:7], off
	s_waitcnt vmcnt(3)
	s_nop 0
	v_lshlrev_b32_e32 v4, 16, v8
	s_waitcnt lgkmcnt(2)
	v_lshlrev_b32_e32 v5, 16, v24
	v_mul_f32_e32 v4, v5, v4
	v_and_b32_e32 v5, 0xffff0000, v24
	v_and_b32_e32 v6, 0xffff0000, v8
	v_mul_f32_e32 v5, v5, v6
	v_cvt_pk_bf16_f32 v4, v4, v5
	v_lshlrev_b32_e32 v5, 16, v9
	v_lshlrev_b32_e32 v6, 16, v25
	v_mul_f32_e32 v5, v6, v5
	v_and_b32_e32 v6, 0xffff0000, v25
	v_and_b32_e32 v7, 0xffff0000, v9
	v_mul_f32_e32 v6, v6, v7
	v_cvt_pk_bf16_f32 v5, v5, v6
	v_lshlrev_b32_e32 v6, 16, v10
	v_lshlrev_b32_e32 v7, 16, v26
	v_mul_f32_e32 v6, v7, v6
	v_and_b32_e32 v7, 0xffff0000, v26
	v_and_b32_e32 v8, 0xffff0000, v10
	v_mul_f32_e32 v7, v7, v8
	v_cvt_pk_bf16_f32 v6, v6, v7
	v_lshlrev_b32_e32 v7, 16, v11
	v_lshlrev_b32_e32 v8, 16, v27
	v_mul_f32_e32 v7, v8, v7
	v_and_b32_e32 v8, 0xffff0000, v27
	v_and_b32_e32 v9, 0xffff0000, v11
	v_mul_f32_e32 v8, v8, v9
	v_cvt_pk_bf16_f32 v7, v7, v8
	v_add_co_u32_e32 v8, vcc, s58, v2
	s_nop 1
	v_addc_co_u32_e32 v9, vcc, 0, v3, vcc
	global_store_dwordx4 v[8:9], v[4:7], off
	s_waitcnt vmcnt(3)
	v_and_b32_e32 v8, 0xffff0000, v14
	v_and_b32_e32 v9, 0xffff0000, v15
	v_lshlrev_b32_e32 v4, 16, v12
	s_waitcnt lgkmcnt(1)
	v_lshlrev_b32_e32 v5, 16, v28
	v_mul_f32_e32 v4, v5, v4
	v_and_b32_e32 v5, 0xffff0000, v28
	v_and_b32_e32 v6, 0xffff0000, v12
	v_mul_f32_e32 v5, v5, v6
	v_cvt_pk_bf16_f32 v4, v4, v5
	v_lshlrev_b32_e32 v5, 16, v13
	v_lshlrev_b32_e32 v6, 16, v29
	v_mul_f32_e32 v5, v6, v5
	v_and_b32_e32 v6, 0xffff0000, v29
	v_and_b32_e32 v7, 0xffff0000, v13
	v_mul_f32_e32 v6, v6, v7
	v_cvt_pk_bf16_f32 v5, v5, v6
	v_lshlrev_b32_e32 v6, 16, v14
	v_lshlrev_b32_e32 v7, 16, v30
	v_mul_f32_e32 v6, v7, v6
	v_and_b32_e32 v7, 0xffff0000, v30
	v_mul_f32_e32 v7, v7, v8
	v_cvt_pk_bf16_f32 v6, v6, v7
	v_lshlrev_b32_e32 v7, 16, v15
	v_lshlrev_b32_e32 v8, 16, v31
	v_mul_f32_e32 v7, v8, v7
	v_and_b32_e32 v8, 0xffff0000, v31
	v_mul_f32_e32 v8, v8, v9
	v_cvt_pk_bf16_f32 v7, v7, v8
	v_add_co_u32_e32 v8, vcc, s59, v2
	s_nop 1
	v_addc_co_u32_e32 v9, vcc, 0, v3, vcc
	global_store_dwordx4 v[8:9], v[4:7], off
	s_waitcnt vmcnt(3)
	v_and_b32_e32 v8, 0xffff0000, v18
	v_and_b32_e32 v9, 0xffff0000, v19
	v_lshlrev_b32_e32 v4, 16, v16
	s_waitcnt lgkmcnt(0)
	v_lshlrev_b32_e32 v5, 16, v32
	v_mul_f32_e32 v4, v5, v4
	v_and_b32_e32 v5, 0xffff0000, v32
	v_and_b32_e32 v6, 0xffff0000, v16
	v_mul_f32_e32 v5, v5, v6
	v_cvt_pk_bf16_f32 v4, v4, v5
	v_lshlrev_b32_e32 v5, 16, v17
	v_lshlrev_b32_e32 v6, 16, v33
	v_mul_f32_e32 v5, v6, v5
	v_and_b32_e32 v6, 0xffff0000, v33
	v_and_b32_e32 v7, 0xffff0000, v17
	v_mul_f32_e32 v6, v6, v7
	v_cvt_pk_bf16_f32 v5, v5, v6
	v_lshlrev_b32_e32 v6, 16, v18
	v_lshlrev_b32_e32 v7, 16, v34
	v_mul_f32_e32 v6, v7, v6
	v_and_b32_e32 v7, 0xffff0000, v34
	v_mul_f32_e32 v7, v7, v8
	v_cvt_pk_bf16_f32 v6, v6, v7
	v_lshlrev_b32_e32 v7, 16, v19
	v_lshlrev_b32_e32 v8, 16, v35
	v_mul_f32_e32 v7, v8, v7
	v_and_b32_e32 v8, 0xffff0000, v35
	v_mul_f32_e32 v8, v8, v9
	v_cvt_pk_bf16_f32 v7, v7, v8
	v_add_co_u32_e32 v8, vcc, s60, v2
	s_nop 1
	v_addc_co_u32_e32 v9, vcc, 0, v3, vcc
	global_store_dwordx4 v[8:9], v[4:7], off
	s_nop 1
	v_add_co_u32_e32 v4, vcc, s62, v36
	s_nop 1
	v_addc_co_u32_e32 v5, vcc, 0, v37, vcc
	global_load_dwordx4 v[4:7], v[4:5], off nt
	v_add_co_u32_e32 v8, vcc, s63, v36
	s_nop 1
	v_addc_co_u32_e32 v9, vcc, 0, v37, vcc
	global_load_dwordx4 v[8:11], v[8:9], off nt
	v_add_co_u32_e32 v12, vcc, s64, v36
	s_nop 1
	v_addc_co_u32_e32 v13, vcc, 0, v37, vcc
	global_load_dwordx4 v[12:15], v[12:13], off nt
	v_add_co_u32_e32 v16, vcc, s65, v36
	s_waitcnt vmcnt(2)
	v_lshlrev_b32_e32 v36, 16, v4
	v_addc_co_u32_e32 v17, vcc, 0, v37, vcc
	global_load_dwordx4 v[16:19], v[16:17], off nt
	ds_read_b128 v[20:23], v38 offset:4352
	ds_read_b128 v[24:27], v38 offset:5440
	ds_read_b128 v[28:31], v38 offset:6528
	ds_read_b128 v[32:35], v38 offset:7616
	v_and_b32_e32 v4, 0xffff0000, v4
	s_waitcnt lgkmcnt(3)
	v_lshlrev_b32_e32 v37, 16, v20
	v_and_b32_e32 v20, 0xffff0000, v20
	v_mul_f32_e32 v36, v37, v36
	v_mul_f32_e32 v4, v20, v4
	v_cvt_pk_bf16_f32 v4, v36, v4
	v_lshlrev_b32_e32 v20, 16, v5
	v_lshlrev_b32_e32 v36, 16, v21
	v_and_b32_e32 v21, 0xffff0000, v21
	v_and_b32_e32 v5, 0xffff0000, v5
	v_mul_f32_e32 v20, v36, v20
	v_mul_f32_e32 v5, v21, v5
	v_cvt_pk_bf16_f32 v5, v20, v5
	v_lshlrev_b32_e32 v20, 16, v6
	v_lshlrev_b32_e32 v21, 16, v22
	v_mul_f32_e32 v20, v21, v20
	v_and_b32_e32 v21, 0xffff0000, v22
	v_and_b32_e32 v6, 0xffff0000, v6
	v_mul_f32_e32 v6, v21, v6
	v_cvt_pk_bf16_f32 v6, v20, v6
	v_lshlrev_b32_e32 v20, 16, v7
	v_lshlrev_b32_e32 v21, 16, v23
	v_mul_f32_e32 v20, v21, v20
	v_and_b32_e32 v21, 0xffff0000, v23
	v_and_b32_e32 v7, 0xffff0000, v7
	v_mul_f32_e32 v7, v21, v7
	v_cvt_pk_bf16_f32 v7, v20, v7
	v_add_co_u32_e32 v20, vcc, s62, v2
	s_nop 1
	v_addc_co_u32_e32 v21, vcc, 0, v3, vcc
	global_store_dwordx4 v[20:21], v[4:7], off
	s_waitcnt vmcnt(3)
	s_nop 0
	v_lshlrev_b32_e32 v4, 16, v8
	s_waitcnt lgkmcnt(2)
	v_lshlrev_b32_e32 v5, 16, v24
	v_mul_f32_e32 v4, v5, v4
	v_and_b32_e32 v5, 0xffff0000, v24
	v_and_b32_e32 v6, 0xffff0000, v8
	v_mul_f32_e32 v5, v5, v6
	v_cvt_pk_bf16_f32 v4, v4, v5
	v_lshlrev_b32_e32 v5, 16, v9
	v_lshlrev_b32_e32 v6, 16, v25
	v_mul_f32_e32 v5, v6, v5
	v_and_b32_e32 v6, 0xffff0000, v25
	v_and_b32_e32 v7, 0xffff0000, v9
	v_mul_f32_e32 v6, v6, v7
	v_cvt_pk_bf16_f32 v5, v5, v6
	v_lshlrev_b32_e32 v6, 16, v10
	v_lshlrev_b32_e32 v7, 16, v26
	v_mul_f32_e32 v6, v7, v6
	v_and_b32_e32 v7, 0xffff0000, v26
	v_and_b32_e32 v8, 0xffff0000, v10
	v_mul_f32_e32 v7, v7, v8
	v_cvt_pk_bf16_f32 v6, v6, v7
	v_lshlrev_b32_e32 v7, 16, v11
	v_lshlrev_b32_e32 v8, 16, v27
	v_mul_f32_e32 v7, v8, v7
	v_and_b32_e32 v8, 0xffff0000, v27
	v_and_b32_e32 v9, 0xffff0000, v11
	v_mul_f32_e32 v8, v8, v9
	v_cvt_pk_bf16_f32 v7, v7, v8
	v_add_co_u32_e32 v8, vcc, s63, v2
	s_nop 1
	v_addc_co_u32_e32 v9, vcc, 0, v3, vcc
	global_store_dwordx4 v[8:9], v[4:7], off
	s_waitcnt vmcnt(3)
	v_and_b32_e32 v8, 0xffff0000, v14
	v_and_b32_e32 v9, 0xffff0000, v15
	v_lshlrev_b32_e32 v4, 16, v12
	s_waitcnt lgkmcnt(1)
	v_lshlrev_b32_e32 v5, 16, v28
	v_mul_f32_e32 v4, v5, v4
	v_and_b32_e32 v5, 0xffff0000, v28
	v_and_b32_e32 v6, 0xffff0000, v12
	v_mul_f32_e32 v5, v5, v6
	v_cvt_pk_bf16_f32 v4, v4, v5
	v_lshlrev_b32_e32 v5, 16, v13
	v_lshlrev_b32_e32 v6, 16, v29
	v_mul_f32_e32 v5, v6, v5
	v_and_b32_e32 v6, 0xffff0000, v29
	v_and_b32_e32 v7, 0xffff0000, v13
	v_mul_f32_e32 v6, v6, v7
	v_cvt_pk_bf16_f32 v5, v5, v6
	v_lshlrev_b32_e32 v6, 16, v14
	v_lshlrev_b32_e32 v7, 16, v30
	v_mul_f32_e32 v6, v7, v6
	v_and_b32_e32 v7, 0xffff0000, v30
	v_mul_f32_e32 v7, v7, v8
	v_cvt_pk_bf16_f32 v6, v6, v7
	v_lshlrev_b32_e32 v7, 16, v15
	v_lshlrev_b32_e32 v8, 16, v31
	v_mul_f32_e32 v7, v8, v7
	v_and_b32_e32 v8, 0xffff0000, v31
	v_mul_f32_e32 v8, v8, v9
	v_cvt_pk_bf16_f32 v7, v7, v8
	v_add_co_u32_e32 v8, vcc, s64, v2
	s_nop 1
	v_addc_co_u32_e32 v9, vcc, 0, v3, vcc
	global_store_dwordx4 v[8:9], v[4:7], off
	s_waitcnt vmcnt(3)
	v_and_b32_e32 v8, 0xffff0000, v18
	v_add_co_u32_e32 v2, vcc, s65, v2
	v_lshlrev_b32_e32 v4, 16, v16
	s_waitcnt lgkmcnt(0)
	v_lshlrev_b32_e32 v5, 16, v32
	v_mul_f32_e32 v4, v5, v4
	v_and_b32_e32 v5, 0xffff0000, v32
	v_and_b32_e32 v6, 0xffff0000, v16
	v_mul_f32_e32 v5, v5, v6
	v_cvt_pk_bf16_f32 v4, v4, v5
	v_lshlrev_b32_e32 v5, 16, v17
	v_lshlrev_b32_e32 v6, 16, v33
	v_mul_f32_e32 v5, v6, v5
	v_and_b32_e32 v6, 0xffff0000, v33
	v_and_b32_e32 v7, 0xffff0000, v17
	v_mul_f32_e32 v6, v6, v7
	v_cvt_pk_bf16_f32 v5, v5, v6
	v_lshlrev_b32_e32 v6, 16, v18
	v_lshlrev_b32_e32 v7, 16, v34
	v_mul_f32_e32 v6, v7, v6
	v_and_b32_e32 v7, 0xffff0000, v34
	v_mul_f32_e32 v7, v7, v8
	v_cvt_pk_bf16_f32 v6, v6, v7
	v_lshlrev_b32_e32 v7, 16, v19
	v_lshlrev_b32_e32 v8, 16, v35
	v_mul_f32_e32 v7, v8, v7
	v_and_b32_e32 v8, 0xffff0000, v35
	v_and_b32_e32 v9, 0xffff0000, v19
	v_addc_co_u32_e32 v3, vcc, 0, v3, vcc
	v_mul_f32_e32 v8, v8, v9
	v_cvt_pk_bf16_f32 v7, v7, v8
	global_store_dwordx4 v[2:3], v[4:7], off
	s_barrier
	s_barrier

.LBB0_845:
	s_mul_i32 s5, s24, 0x1800
	s_mul_hi_i32 s4, s24, 0x1800
	s_add_u32 s5, s35, s5
	s_addc_u32 s4, s38, s4
	s_mul_i32 s6, s69, 0x180
	s_add_u32 s28, s5, s6
	s_addc_u32 s29, s4, 0
	s_ashr_i32 s27, s26, 31
	s_lshl_b64 s[6:7], s[26:27], 13
	s_add_u32 s4, s39, s6
	s_addc_u32 s5, s47, s7
	s_lshl_b32 s30, s69, 9
	s_add_u32 s4, s4, s30
	s_addc_u32 s5, s5, 0
	s_lshl_b64 s[26:27], s[26:27], 7
	s_waitcnt vmcnt(0)
	v_mov_b32_e32 v40, v0
	s_add_u32 s26, s48, s26
	s_addc_u32 s27, s49, s27
	v_readfirstlane_b32 s31, v40
	s_ashr_i32 s70, s31, 6
	v_and_b32_e32 v163, 31, v40
	s_lshl_b32 s68, s70, 5
	v_bfe_u32 v182, v40, 5, 1
	v_or_b32_e32 v4, s68, v163
	v_mov_b64_e32 v[2:3], s[28:29]
	s_movk_i32 s25, 0x1800
	v_mad_i64_i32 v[2:3], s[28:29], v4, s25, v[2:3]
	v_lshlrev_b32_e32 v166, 4, v182
	v_mov_b32_e32 v167, v165
	v_lshl_add_u64 v[2:3], v[2:3], 0, v[166:167]
	global_load_dwordx4 v[142:145], v[2:3], off nt
	global_load_dwordx4 v[138:141], v[2:3], off offset:32 nt
	global_load_dwordx4 v[134:137], v[2:3], off offset:64 nt
	global_load_dwordx4 v[130:133], v[2:3], off offset:96 nt
	global_load_dwordx4 v[126:129], v[2:3], off offset:128 nt
	global_load_dwordx4 v[122:125], v[2:3], off offset:160 nt
	global_load_dwordx4 v[118:121], v[2:3], off offset:192 nt
	global_load_dwordx4 v[114:117], v[2:3], off offset:224 nt
	global_load_dwordx4 v[110:113], v[2:3], off offset:256 nt
	global_load_dwordx4 v[106:109], v[2:3], off offset:288 nt
	global_load_dwordx4 v[102:105], v[2:3], off offset:320 nt
	global_load_dwordx4 v[98:101], v[2:3], off offset:352 nt
	v_mov_b32_e32 v2, s31
	s_movk_i32 s25, 0xffc0
	v_bfi_b32 v2, s25, v2, v40
	v_mul_hi_i32 v3, v2, s53
	v_lshrrev_b32_e32 v4, 31, v3
	v_ashrrev_i32_e32 v3, 2, v3
	v_add_u32_e32 v4, v3, v4
	v_mad_u64_u32 v[6:7], s[28:29], v4, s54, v[2:3]
	v_lshrrev_b32_e32 v3, 1, v4
	v_bitop3_b32 v3, v6, v3, 7 bitop3:0x78
	v_cmp_lt_i32_e32 vcc, 15, v3
	v_ashrrev_i32_e32 v5, 31, v4
	v_lshlrev_b32_e32 v6, 4, v3
	s_and_saveexec_b64 s[28:29], vcc
	s_xor_b64 s[28:29], exec, s[28:29]
	v_lshlrev_b64 v[4:5], 7, v[4:5]
	v_lshl_add_u64 v[4:5], s[26:27], 0, v[4:5]
	v_add_u32_e32 v164, 0xffffff00, v6
	v_lshl_add_u64 v[34:35], v[4:5], 0, v[164:165]
	s_or_saveexec_b64 s[28:29], s[28:29]
	v_mov_b64_e32 v[168:169], 0x2000
	s_xor_b64 exec, exec, s[28:29]
	v_lshlrev_b64 v[4:5], 13, v[4:5]
	v_lshl_add_u64 v[4:5], s[4:5], 0, v[4:5]
	v_ashrrev_i32_e32 v7, 31, v6
	v_lshl_add_u64 v[34:35], v[4:5], 0, v[6:7]
	v_mov_b64_e32 v[168:169], 0x80000
	s_or_b64 exec, exec, s[28:29]
	v_add_u32_e32 v6, 0x200, v2
	v_mul_hi_i32 v3, v6, s53
	v_lshrrev_b32_e32 v4, 31, v3
	v_ashrrev_i32_e32 v3, 2, v3
	v_add_u32_e32 v4, v3, v4
	v_mad_u64_u32 v[6:7], s[28:29], v4, s54, v[6:7]
	v_lshrrev_b32_e32 v3, 1, v4
	v_bitop3_b32 v3, v6, v3, 7 bitop3:0x78
	v_cmp_lt_i32_e32 vcc, 15, v3
	v_ashrrev_i32_e32 v5, 31, v4
	v_lshlrev_b32_e32 v6, 4, v3
	s_and_saveexec_b64 s[28:29], vcc
	s_xor_b64 s[28:29], exec, s[28:29]
	v_lshlrev_b64 v[4:5], 7, v[4:5]
	v_lshl_add_u64 v[4:5], s[26:27], 0, v[4:5]
	v_add_u32_e32 v164, 0xffffff00, v6
	v_lshl_add_u64 v[36:37], v[4:5], 0, v[164:165]
	s_or_saveexec_b64 s[28:29], s[28:29]
	v_mov_b64_e32 v[170:171], 0x2000
	s_xor_b64 exec, exec, s[28:29]
	v_lshlrev_b64 v[4:5], 13, v[4:5]
	v_lshl_add_u64 v[4:5], s[4:5], 0, v[4:5]
	v_ashrrev_i32_e32 v7, 31, v6
	v_lshl_add_u64 v[36:37], v[4:5], 0, v[6:7]
	v_mov_b64_e32 v[170:171], 0x80000
	s_or_b64 exec, exec, s[28:29]
	v_add_u32_e32 v4, 0x400, v2
	v_mul_hi_i32 v2, v4, s53
	v_lshrrev_b32_e32 v3, 31, v2
	v_ashrrev_i32_e32 v2, 2, v2
	v_add_u32_e32 v2, v2, v3
	v_mad_u64_u32 v[4:5], s[28:29], v2, s54, v[4:5]
	v_lshrrev_b32_e32 v3, 1, v2
	v_bitop3_b32 v4, v4, v3, 7 bitop3:0x78
	v_cmp_lt_i32_e32 vcc, 15, v4
	v_ashrrev_i32_e32 v3, 31, v2
	v_lshlrev_b32_e32 v4, 4, v4
	s_and_saveexec_b64 s[28:29], vcc
	s_xor_b64 s[28:29], exec, s[28:29]
	v_lshlrev_b64 v[2:3], 7, v[2:3]
	v_lshl_add_u64 v[2:3], s[26:27], 0, v[2:3]
	v_add_u32_e32 v164, 0xffffff00, v4
	v_lshl_add_u64 v[38:39], v[2:3], 0, v[164:165]
	s_or_saveexec_b64 s[26:27], s[28:29]
	v_mov_b64_e32 v[172:173], 0x2000
	s_xor_b64 exec, exec, s[26:27]
	v_lshlrev_b64 v[2:3], 13, v[2:3]
	v_lshl_add_u64 v[2:3], s[4:5], 0, v[2:3]
	v_ashrrev_i32_e32 v5, 31, v4
	v_lshl_add_u64 v[38:39], v[2:3], 0, v[4:5]
	v_mov_b64_e32 v[172:173], 0x80000
	s_or_b64 exec, exec, s[26:27]
	s_lshl_b32 s80, s70, 10
	s_lshl_b32 s26, s70, 1
	s_ashr_i32 s27, s31, 4
	v_lshrrev_b32_e32 v3, 1, v163
	s_and_b32 s28, s27, -16
	v_and_b32_e32 v42, 8, v3
	s_lshr_b32 s27, s27, 1
	v_and_or_b32 v3, s26, 2, v182
	s_add_i32 s26, s80, 0
	s_ashr_i32 s25, s24, 31
	s_and_b32 s72, s31, 0xffffffc0
	s_and_b32 s29, s27, 4
	s_add_i32 m0, s26, 0xc000
	v_bfe_u32 v41, v163, 2, 2
	v_lshlrev_b32_e32 v4, 4, v40
	s_cmp_lg_u32 0, -1
	v_or_b32_e32 v2, s28, v41
	v_and_b32_e32 v43, 48, v4
	s_cselect_b32 s26, 0, 0
	v_or3_b32 v2, v2, v42, s29
	v_lshl_or_b32 v3, v3, 6, v43
	s_add_i32 s76, s80, s26
	v_lshl_or_b32 v164, v2, 13, v3
	global_load_lds_dwordx4 v[34:35], off
	s_add_i32 m0, s76, 0xe000
	v_lshl_add_u64 v[8:9], s[4:5], 0, v[164:165]
	global_load_lds_dwordx4 v[36:37], off
	s_add_i32 m0, s76, 0x10000
	s_mov_b64 s[4:5], 0x100
	global_load_lds_dwordx4 v[38:39], off
	v_lshl_add_u64 v[10:11], v[8:9], 0, s[4:5]
	s_mov_b32 m0, s76
	s_mov_b64 s[4:5], 0x40100
	global_load_lds_dwordx4 v[10:11], off
	v_lshl_add_u64 v[10:11], v[8:9], 0, s[4:5]
	s_add_i32 m0, s76, 0x2000
	v_lshl_add_u64 v[2:3], v[34:35], 0, v[168:169]
	global_load_lds_dwordx4 v[10:11], off
	s_add_i32 m0, s76, 0x12000
	v_lshl_add_u64 v[4:5], v[36:37], 0, v[170:171]
	global_load_lds_dwordx4 v[2:3], off
	s_add_i32 m0, s76, 0x14000
	v_lshl_add_u64 v[6:7], v[38:39], 0, v[172:173]
	global_load_lds_dwordx4 v[4:5], off
	s_add_i32 m0, s76, 0x16000
	s_mov_b64 s[4:5], 0x80100
	global_load_lds_dwordx4 v[6:7], off
	s_add_i32 m0, s76, 0x4000
	v_lshl_add_u64 v[10:11], v[8:9], 0, s[4:5]
	s_mov_b64 s[4:5], 0xc0100
	global_load_lds_dwordx4 v[10:11], off
	v_lshl_add_u64 v[8:9], v[8:9], 0, s[4:5]
	s_add_i32 m0, s76, 0x6000
	v_lshl_add_u64 v[2:3], v[2:3], 0, v[168:169]
	global_load_lds_dwordx4 v[8:9], off
	s_add_i32 m0, s76, 0x18000
	v_lshl_add_u64 v[4:5], v[4:5], 0, v[170:171]
	global_load_lds_dwordx4 v[2:3], off
	s_add_i32 m0, s76, 0x1a000
	v_lshlrev_b32_e32 v2, 3, v163
	s_movk_i32 s4, 0x180
	v_lshl_add_u64 v[6:7], v[6:7], 0, v[172:173]
	global_load_lds_dwordx4 v[4:5], off
	s_add_i32 m0, s76, 0x1c000
	v_and_b32_e32 v64, 0x70, v2
	v_mad_u32_u24 v65, v163, s4, 0
	global_load_lds_dwordx4 v[6:7], off
	v_xad_u32 v6, v166, v64, v65
	s_waitcnt vmcnt(0)
	s_waitcnt vmcnt(0) lgkmcnt(0)
	s_barrier
	ds_read_b128 v[2:5], v6 offset:49152
	ds_read_b128 v[6:9], v6 offset:61440
	s_waitcnt lgkmcnt(1)
	v_mfma_f32_32x32x16_bf16 v[18:33], v[2:5], v[142:145], 0
	v_or_b32_e32 v44, 32, v166
	v_xad_u32 v45, v44, v64, v65
	ds_read_b128 v[46:49], v45 offset:49152
	ds_read_b128 v[50:53], v45 offset:61440
	v_or_b32_e32 v45, 64, v166
	s_waitcnt lgkmcnt(2)
	v_mfma_f32_32x32x16_bf16 v[2:17], v[6:9], v[142:145], 0
	s_waitcnt lgkmcnt(1)
	v_mfma_f32_32x32x16_bf16 v[18:33], v[46:49], v[138:141], v[18:33]
	s_waitcnt lgkmcnt(0)
	v_mfma_f32_32x32x16_bf16 v[2:17], v[50:53], v[138:141], v[2:17]
	v_xad_u32 v50, v45, v64, v65
	ds_read_b128 v[46:49], v50 offset:49152
	ds_read_b128 v[50:53], v50 offset:61440
	s_waitcnt lgkmcnt(1)
	v_mfma_f32_32x32x16_bf16 v[18:33], v[46:49], v[134:137], v[18:33]
	v_or_b32_e32 v46, 0x60, v166
	v_xad_u32 v47, v46, v64, v65
	s_waitcnt lgkmcnt(0)
	v_mfma_f32_32x32x16_bf16 v[2:17], v[50:53], v[134:137], v[2:17]
	ds_read_b128 v[48:51], v47 offset:49152
	ds_read_b128 v[52:55], v47 offset:61440
	v_or_b32_e32 v47, 0x80, v166
	s_waitcnt lgkmcnt(1)
	v_mfma_f32_32x32x16_bf16 v[18:33], v[48:51], v[130:133], v[18:33]
	s_waitcnt lgkmcnt(0)
	v_mfma_f32_32x32x16_bf16 v[2:17], v[52:55], v[130:133], v[2:17]
	v_xad_u32 v52, v47, v64, v65
	ds_read_b128 v[48:51], v52 offset:49152
	ds_read_b128 v[52:55], v52 offset:61440
	s_waitcnt lgkmcnt(1)
	v_mfma_f32_32x32x16_bf16 v[18:33], v[48:51], v[126:129], v[18:33]
	v_or_b32_e32 v48, 0xa0, v166
	v_xad_u32 v49, v48, v64, v65
	s_waitcnt lgkmcnt(0)
	v_mfma_f32_32x32x16_bf16 v[2:17], v[52:55], v[126:129], v[2:17]
	ds_read_b128 v[50:53], v49 offset:49152
	ds_read_b128 v[54:57], v49 offset:61440
	v_or_b32_e32 v49, 0xc0, v166
	s_waitcnt lgkmcnt(1)
	v_mfma_f32_32x32x16_bf16 v[18:33], v[50:53], v[122:125], v[18:33]
	s_waitcnt lgkmcnt(0)
	v_mfma_f32_32x32x16_bf16 v[2:17], v[54:57], v[122:125], v[2:17]
	v_xad_u32 v54, v49, v64, v65
	ds_read_b128 v[50:53], v54 offset:49152
	ds_read_b128 v[54:57], v54 offset:61440
	s_waitcnt lgkmcnt(1)
	v_mfma_f32_32x32x16_bf16 v[18:33], v[50:53], v[118:121], v[18:33]
	v_or_b32_e32 v50, 0xe0, v166
	v_xad_u32 v51, v50, v64, v65
	s_waitcnt lgkmcnt(0)
	v_mfma_f32_32x32x16_bf16 v[2:17], v[54:57], v[118:121], v[2:17]
	ds_read_b128 v[52:55], v51 offset:49152
	ds_read_b128 v[56:59], v51 offset:61440
	v_or_b32_e32 v51, 0x100, v166
	s_waitcnt lgkmcnt(1)
	v_mfma_f32_32x32x16_bf16 v[18:33], v[52:55], v[114:117], v[18:33]
	s_waitcnt lgkmcnt(0)
	v_mfma_f32_32x32x16_bf16 v[2:17], v[56:59], v[114:117], v[2:17]
	v_xad_u32 v56, v51, v64, v65
	ds_read_b128 v[52:55], v56 offset:49152
	ds_read_b128 v[56:59], v56 offset:61440
	s_waitcnt lgkmcnt(1)
	v_mfma_f32_32x32x16_bf16 v[18:33], v[52:55], v[110:113], v[18:33]
	v_or_b32_e32 v52, 0x120, v166
	v_xad_u32 v53, v52, v64, v65
	s_waitcnt lgkmcnt(0)
	v_mfma_f32_32x32x16_bf16 v[2:17], v[56:59], v[110:113], v[2:17]
	ds_read_b128 v[54:57], v53 offset:49152
	ds_read_b128 v[58:61], v53 offset:61440
	v_or_b32_e32 v53, 0x140, v166
	s_waitcnt lgkmcnt(1)
	v_mfma_f32_32x32x16_bf16 v[18:33], v[54:57], v[106:109], v[18:33]
	v_xad_u32 v54, v53, v64, v65
	s_waitcnt lgkmcnt(0)
	v_mfma_f32_32x32x16_bf16 v[2:17], v[58:61], v[106:109], v[2:17]
	ds_read_b128 v[56:59], v54 offset:49152
	ds_read_b128 v[60:63], v54 offset:61440
	v_or_b32_e32 v54, 0x160, v166
	v_xad_u32 v55, v54, v64, v65
	s_waitcnt lgkmcnt(1)
	v_mfma_f32_32x32x16_bf16 v[18:33], v[56:59], v[102:105], v[18:33]
	ds_read_b128 v[56:59], v55 offset:49152
	ds_read_b128 v[64:67], v55 offset:61440
	s_waitcnt lgkmcnt(1)
	v_mfma_f32_32x32x16_bf16 v[18:33], v[56:59], v[98:101], v[18:33]
	v_mfma_f32_32x32x16_bf16 v[2:17], v[60:63], v[102:105], v[2:17]
	s_nop 10
	v_max_f32_e32 v55, v19, v19
	v_max_f32_e32 v56, v18, v18
	v_max_f32_e32 v55, v56, v55
	v_max3_f32 v55, v55, v20, v21
	v_max3_f32 v55, v55, v22, v23
	v_max3_f32 v55, v55, v24, v25
	v_max3_f32 v55, v55, v26, v27
	s_waitcnt lgkmcnt(0)
	v_mfma_f32_32x32x16_bf16 v[2:17], v[64:67], v[98:101], v[2:17]
	v_max3_f32 v55, v55, v28, v29
	v_max3_f32 v55, v55, v30, v31
	v_max3_f32 v55, v55, v32, v33
	s_nop 8
	v_max3_f32 v55, v55, v2, v3
	v_max3_f32 v55, v55, v4, v5
	v_max3_f32 v55, v55, v6, v7
	v_max3_f32 v55, v55, v8, v9
	v_max3_f32 v55, v55, v10, v11
	v_max3_f32 v55, v55, v12, v13
	v_max3_f32 v55, v55, v14, v15
	v_max3_f32 v55, v55, v16, v17
	v_mov_b32_e32 v56, v55
	s_nop 1
	v_permlane32_swap_b32_e32 v55, v56
	v_max_f32_e32 v56, v56, v56
	v_max_f32_e32 v55, v55, v55
	v_max_f32_e32 v55, v55, v56
	v_add_f32_e32 v56, 0x7149f2ca, v55
	v_cmp_ge_f32_e32 vcc, s56, v56
	s_cmp_eq_u64 vcc, exec
	v_max_f32_e32 v55, 0xf149f2ca, v55
	s_cselect_b64 s[4:5], -1, 0
	v_cndmask_b32_e64 v194, v55, v1, s[4:5]
	v_mul_f32_e32 v56, 0xbdd53b94, v194
	v_fmamk_f32 v18, v18, 0x3dd53b94, v56
	v_fmamk_f32 v19, v19, 0x3dd53b94, v56
	v_fmamk_f32 v20, v20, 0x3dd53b94, v56
	v_fmamk_f32 v21, v21, 0x3dd53b94, v56
	v_fmamk_f32 v22, v22, 0x3dd53b94, v56
	v_fmamk_f32 v23, v23, 0x3dd53b94, v56
	v_fmamk_f32 v24, v24, 0x3dd53b94, v56
	v_fmamk_f32 v25, v25, 0x3dd53b94, v56
	v_fmamk_f32 v26, v26, 0x3dd53b94, v56
	v_fmamk_f32 v27, v27, 0x3dd53b94, v56
	v_fmamk_f32 v28, v28, 0x3dd53b94, v56
	v_fmamk_f32 v29, v29, 0x3dd53b94, v56
	v_fmamk_f32 v30, v30, 0x3dd53b94, v56
	v_fmamk_f32 v31, v31, 0x3dd53b94, v56
	v_fmamk_f32 v32, v32, 0x3dd53b94, v56
	v_fmamk_f32 v33, v33, 0x3dd53b94, v56
	v_fmamk_f32 v2, v2, 0x3dd53b94, v56
	v_fmamk_f32 v3, v3, 0x3dd53b94, v56
	v_fmamk_f32 v4, v4, 0x3dd53b94, v56
	v_fmamk_f32 v5, v5, 0x3dd53b94, v56
	v_fmamk_f32 v6, v6, 0x3dd53b94, v56
	v_fmamk_f32 v7, v7, 0x3dd53b94, v56
	v_fmamk_f32 v8, v8, 0x3dd53b94, v56
	v_fmamk_f32 v9, v9, 0x3dd53b94, v56
	v_fmamk_f32 v10, v10, 0x3dd53b94, v56
	v_fmamk_f32 v11, v11, 0x3dd53b94, v56
	v_fmamk_f32 v12, v12, 0x3dd53b94, v56
	v_fmamk_f32 v13, v13, 0x3dd53b94, v56
	v_fmamk_f32 v14, v14, 0x3dd53b94, v56
	v_fmamk_f32 v15, v15, 0x3dd53b94, v56
	v_fmamk_f32 v16, v16, 0x3dd53b94, v56
	v_fmac_f32_e32 v56, 0x3dd53b94, v17
	v_exp_f32_e32 v17, v18
	v_exp_f32_e32 v18, v19
	v_exp_f32_e32 v19, v20
	v_exp_f32_e32 v20, v21
	v_exp_f32_e32 v21, v22
	v_exp_f32_e32 v22, v23
	v_exp_f32_e32 v23, v24
	v_exp_f32_e32 v24, v25
	v_exp_f32_e32 v25, v26
	v_exp_f32_e32 v26, v27
	v_exp_f32_e32 v27, v28
	v_exp_f32_e32 v28, v29
	v_exp_f32_e32 v29, v30
	v_exp_f32_e32 v30, v31
	v_exp_f32_e32 v31, v32
	v_exp_f32_e32 v32, v33
	v_exp_f32_e32 v33, v2
	v_add_f32_e32 v2, 0, v17
	v_add_f32_e32 v2, v18, v2
	v_add_f32_e32 v2, v19, v2
	v_add_f32_e32 v2, v20, v2
	v_add_f32_e32 v2, v21, v2
	v_add_f32_e32 v2, v22, v2
	v_add_f32_e32 v2, v23, v2
	v_add_f32_e32 v2, v24, v2
	v_add_f32_e32 v2, v25, v2
	v_add_f32_e32 v2, v26, v2
	v_add_f32_e32 v2, v27, v2
	v_add_f32_e32 v2, v28, v2
	v_add_f32_e32 v2, v29, v2
	v_exp_f32_e32 v57, v3
	v_add_f32_e32 v2, v30, v2
	v_exp_f32_e32 v4, v4
	v_add_f32_e32 v2, v31, v2
	v_exp_f32_e32 v5, v5
	v_add_f32_e32 v2, v32, v2
	v_exp_f32_e32 v6, v6
	v_add_f32_e32 v2, v33, v2
	v_exp_f32_e32 v7, v7
	v_add_f32_e32 v2, v57, v2
	v_exp_f32_e32 v8, v8
	v_add_f32_e32 v2, v4, v2
	v_exp_f32_e32 v9, v9
	v_add_f32_e32 v2, v5, v2
	v_exp_f32_e32 v10, v10
	v_add_f32_e32 v2, v6, v2
	v_exp_f32_e32 v11, v11
	v_add_f32_e32 v2, v7, v2
	v_exp_f32_e32 v12, v12
	v_add_f32_e32 v2, v8, v2
	v_exp_f32_e32 v13, v13
	v_add_f32_e32 v2, v9, v2
	v_exp_f32_e32 v14, v14
	v_add_f32_e32 v2, v10, v2
	v_exp_f32_e32 v15, v15
	v_add_f32_e32 v2, v11, v2
	v_exp_f32_e32 v16, v16
	v_add_f32_e32 v2, v12, v2
	v_exp_f32_e32 v56, v56
	v_add_f32_e32 v2, v13, v2
	v_add_f32_e32 v2, v14, v2
	v_add_f32_e32 v2, v15, v2
	v_add_f32_e32 v2, v16, v2
	v_add_f32_e32 v2, v56, v2
	s_cmpk_lt_u32 s31, 0x100
	v_mov_b32_e32 v3, v2
	v_cvt_pk_bf16_f32 v146, v17, v18
	v_cvt_pk_bf16_f32 v147, v19, v20
	v_cvt_pk_bf16_f32 v148, v21, v22
	v_cvt_pk_bf16_f32 v149, v23, v24
	v_cvt_pk_bf16_f32 v150, v25, v26
	v_cvt_pk_bf16_f32 v151, v27, v28
	v_cvt_pk_bf16_f32 v152, v29, v30
	v_cvt_pk_bf16_f32 v153, v31, v32
	v_cvt_pk_bf16_f32 v158, v33, v57
	v_cvt_pk_bf16_f32 v159, v4, v5
	v_cvt_pk_bf16_f32 v160, v6, v7
	v_cvt_pk_bf16_f32 v161, v8, v9
	v_cvt_pk_bf16_f32 v154, v10, v11
	v_cvt_pk_bf16_f32 v155, v12, v13
	v_cvt_pk_bf16_f32 v156, v14, v15
	v_cvt_pk_bf16_f32 v157, v16, v56
	s_cselect_b64 s[26:27], -1, 0
	s_nop 0
	v_permlane32_swap_b32_e32 v2, v3
	v_permlane32_swap_b32_e32 v146, v148
	v_permlane32_swap_b32_e32 v147, v149
	v_permlane32_swap_b32_e32 v150, v152
	v_permlane32_swap_b32_e32 v151, v153
	v_permlane32_swap_b32_e32 v158, v160
	v_permlane32_swap_b32_e32 v159, v161
	v_permlane32_swap_b32_e32 v154, v156
	v_permlane32_swap_b32_e32 v155, v157
	s_and_b64 vcc, exec, s[26:27]
	s_cbranch_vccnz .LBB0_859
	s_barrier

.LBB0_1208:
	s_mul_hi_i32 s10, s19, 0x3e0f83e1
	s_lshr_b32 s11, s10, 31
	s_ashr_i32 s10, s10, 5
	s_add_i32 s10, s10, s11
	s_mul_hi_i32 s11, s19, 0xa57eb503
	s_add_i32 s11, s11, s19
	s_lshr_b32 s20, s11, 31
	s_ashr_i32 s11, s11, 9
	s_mul_i32 s22, s10, 0xffffdf00
	s_add_i32 s11, s11, s20
	s_add_i32 s22, s15, s22
	s_mul_i32 s21, s11, 0x2100
	s_ashr_i32 s23, s22, 31
	s_mul_hi_i32 s20, s11, 0x2100
	s_add_u32 s68, s21, s22
	s_addc_u32 s69, s20, s23
	v_lshl_add_u64 v[2:3], s[68:69], 0, v[66:67]
	v_lshlrev_b64 v[2:3], 7, v[2:3]
	v_lshl_add_u64 v[2:3], v[70:71], 0, v[2:3]
	s_barrier
	global_load_dwordx4 v[2:5], v[2:3], off nt
	v_add_u32_e32 v6, 0, v1
	s_andn2_b64 vcc, exec, s[6:7]
	s_waitcnt vmcnt(0)
	ds_write_b128 v6, v[2:5]
	s_waitcnt lgkmcnt(0)
	s_barrier
	s_cbranch_vccnz .LBB0_1207
	s_mul_hi_i32 s20, s10, 0x2aaaaaab
	s_lshr_b32 s21, s20, 31
	s_add_i32 s20, s20, s21
	s_mul_i32 s20, s20, 6
	s_sub_i32 s20, s10, s20
	s_lshl_b32 s76, s20, 8
	s_ashr_i32 s77, s76, 31
	v_lshl_add_u64 v[2:3], s[76:77], 1, v[72:73]
	v_or_b32_e32 v4, s68, v74
	v_mad_u64_u32 v[4:5], s[72:73], v4, s14, v[2:3]
	s_mul_i32 s21, s69, 0x1800
	v_add_u32_e32 v5, s21, v5
	global_load_dwordx4 v[34:37], v[4:5], off nt
	global_load_dwordx4 v[38:41], v[4:5], off offset:3072 nt
	v_or_b32_e32 v4, s68, v76
	v_mad_u64_u32 v[4:5], s[72:73], v4, s14, v[2:3]
	v_add_u32_e32 v5, s21, v5
	global_load_dwordx4 v[42:45], v[4:5], off nt
	global_load_dwordx4 v[46:49], v[4:5], off offset:3072 nt
	v_or_b32_e32 v4, s68, v78
	v_mad_u64_u32 v[4:5], s[72:73], v4, s14, v[2:3]
	v_add_u32_e32 v5, s21, v5
	global_load_dwordx4 v[50:53], v[4:5], off nt
	global_load_dwordx4 v[54:57], v[4:5], off offset:3072 nt
	v_lshl_add_u64 v[4:5], s[68:69], 0, v[80:81]
	v_mad_u64_u32 v[2:3], s[68:69], v4, s14, v[2:3]
	v_mov_b32_e32 v4, v3
	v_mad_u64_u32 v[4:5], s[68:69], v5, s14, v[4:5]
	v_mov_b32_e32 v3, v4
	global_load_dwordx4 v[58:61], v[2:3], off nt
	global_load_dwordx4 v[62:65], v[2:3], off offset:3072 nt
	v_and_b32_e32 v3, 64, v152
	v_xor_b32_e32 v2, 32, v152
	v_add_u32_e32 v3, 64, v3
	v_add_u32_e32 v144, s76, v82
	v_cmp_lt_i32_e32 vcc, v2, v3
	v_ashrrev_i32_e32 v145, 31, v144
	v_lshl_add_u64 v[4:5], v[144:145], 2, s[74:75]
	v_cndmask_b32_e32 v2, v152, v2, vcc
	v_lshlrev_b32_e32 v156, 2, v2
	v_lshl_add_u64 v[2:3], s[76:77], 2, v[86:87]
	v_lshlrev_b32_e32 v68, 2, v88
	global_load_dword v8, v[4:5], off nt
	v_lshl_add_u64 v[4:5], v[2:3], 0, v[68:69]
	global_load_dword v6, v[4:5], off nt
	s_movk_i32 s21, 0x3000
	v_lshlrev_b32_e32 v142, 2, v90
	v_mov_b32_e32 v143, v69
	v_lshlrev_b32_e32 v146, 2, v92
	v_mov_b32_e32 v147, v69
	v_lshlrev_b32_e32 v148, 2, v94
	v_mov_b32_e32 v149, v69
	s_mulk_i32 s11, 0x630
	s_mulk_i32 s20, 0x108
	s_add_i32 s11, s11, s20
	s_mulk_i32 s10, 0x108
	s_sub_i32 s20, s11, s10
	s_add_i32 s72, s17, s20
	s_waitcnt vmcnt(0)
	v_mul_f32_e32 v173, 0x3fb8aa3b, v6
	v_add_co_u32_e32 v6, vcc, s21, v4
	s_mov_b32 s21, 0x9000
	s_nop 0
	v_addc_co_u32_e32 v7, vcc, 0, v5, vcc
	global_load_dword v6, v[6:7], off nt
	s_waitcnt vmcnt(0)
	v_mul_f32_e32 v172, 0x3fb8aa3b, v6
	v_lshl_add_u64 v[6:7], v[2:3], 0, v[142:143]
	global_load_dword v6, v[6:7], off nt
	s_waitcnt vmcnt(0)
	v_mul_f32_e32 v171, 0x3fb8aa3b, v6
	v_add_co_u32_e32 v6, vcc, s21, v4
	s_mov_b32 s21, 0xf000
	s_nop 0
	v_addc_co_u32_e32 v7, vcc, 0, v5, vcc
	global_load_dword v6, v[6:7], off nt
	s_waitcnt vmcnt(0)
	v_mul_f32_e32 v170, 0x3fb8aa3b, v6
	v_lshl_add_u64 v[6:7], v[2:3], 0, v[146:147]
	global_load_dword v6, v[6:7], off nt
	v_lshl_add_u64 v[2:3], v[2:3], 0, v[148:149]
	global_load_dword v2, v[2:3], off nt
	s_waitcnt vmcnt(1)
	v_mul_f32_e32 v169, 0x3fb8aa3b, v6
	v_add_co_u32_e32 v6, vcc, s21, v4
	s_mov_b32 s21, 0x15000
	s_nop 0
	v_addc_co_u32_e32 v7, vcc, 0, v5, vcc
	s_waitcnt vmcnt(0)
	v_mul_f32_e32 v167, 0x3fb8aa3b, v2
	v_add_co_u32_e32 v2, vcc, s21, v4
	global_load_dword v6, v[6:7], off nt
	s_nop 0
	v_addc_co_u32_e32 v3, vcc, 0, v5, vcc
	global_load_dword v2, v[2:3], off nt
	ds_read2_b32 v[158:159], v75 offset1:2
	ds_read2_b32 v[160:161], v75 offset0:4 offset1:6
	ds_read2_b32 v[164:165], v75 offset0:8 offset1:10
	ds_read2_b32 v[174:175], v75 offset0:12 offset1:14
	s_add_i32 vcc_lo, s72, 0xfffff39f
	s_waitcnt vmcnt(1)
	v_mul_f32_e32 v168, 0x3fb8aa3b, v6
	s_waitcnt vmcnt(0)
	v_mul_f32_e32 v166, 0x3fb8aa3b, v2
	v_mul_f32_e32 v2, 0x3fb8aa3b, v8
	v_mov_b32_e32 v3, v2
	v_mov_b32_e32 v4, v2
	v_mov_b32_e32 v5, v2
	v_mov_b32_e32 v6, v2
	v_mov_b32_e32 v7, v2
	v_mov_b32_e32 v8, v2
	v_mov_b32_e32 v9, v2
	v_mov_b32_e32 v10, v2
	v_mov_b32_e32 v11, v2
	v_mov_b32_e32 v12, v2
	v_mov_b32_e32 v13, v2
	v_mov_b32_e32 v14, v2
	v_mov_b32_e32 v15, v2
	v_mov_b32_e32 v16, v2
	v_mov_b32_e32 v17, v2
	s_waitcnt lgkmcnt(3)
	s_nop 0
	v_mfma_f32_32x32x2_f32 v[18:33], v158, v173, v[2:17]
	v_mfma_f32_32x32x2_f32 v[18:33], v159, v172, v[18:33]
	s_waitcnt lgkmcnt(2)
	v_mfma_f32_32x32x2_f32 v[18:33], v160, v171, v[18:33]
	v_mfma_f32_32x32x2_f32 v[18:33], v161, v170, v[18:33]
	s_waitcnt lgkmcnt(1)
	v_mfma_f32_32x32x2_f32 v[18:33], v164, v169, v[18:33]
	v_mfma_f32_32x32x2_f32 v[18:33], v165, v168, v[18:33]
	s_waitcnt lgkmcnt(0)
	v_mfma_f32_32x32x2_f32 v[18:33], v174, v167, v[18:33]
	v_mfma_f32_32x32x2_f32 v[18:33], v175, v166, v[18:33]
	s_nop 15
	s_nop 1
	v_max_f32_e32 v143, v18, v18
	v_exp_f32_e64 v18, -|v18|
	v_min_f32_e32 v143, 0, v143
	v_add_f32_e32 v18, 1.0, v18
	v_log_f32_e32 v18, v18
	s_nop 0
	v_sub_f32_e32 v18, v143, v18
	v_mul_f32_e32 v143, 0x3d800000, v18
	v_max_f32_e32 v18, v19, v19
	v_exp_f32_e64 v19, -|v19|
	v_min_f32_e32 v18, 0, v18
	v_add_f32_e32 v19, 1.0, v19
	v_log_f32_e32 v19, v19
	s_nop 0
	v_sub_f32_e32 v18, v18, v19
	v_max_f32_e32 v19, v20, v20
	v_exp_f32_e64 v20, -|v20|
	v_min_f32_e32 v19, 0, v19
	v_add_f32_e32 v20, 1.0, v20
	v_log_f32_e32 v20, v20
	s_nop 0
	v_sub_f32_e32 v19, v19, v20
	v_max_f32_e32 v20, v21, v21
	v_exp_f32_e64 v21, -|v21|
	v_min_f32_e32 v20, 0, v20
	v_add_f32_e32 v21, 1.0, v21
	v_log_f32_e32 v21, v21
	s_nop 0
	v_sub_f32_e32 v147, v20, v21
	v_exp_f32_e64 v21, -|v22|
	v_max_f32_e32 v20, v22, v22
	v_exp_f32_e64 v22, -|v23|
	v_min_f32_e32 v20, 0, v20
	v_add_f32_e32 v21, 1.0, v21
	v_log_f32_e32 v21, v21
	v_add_f32_e32 v22, 1.0, v22
	v_log_f32_e32 v22, v22
	v_sub_f32_e32 v20, v20, v21
	v_max_f32_e32 v21, v23, v23
	v_min_f32_e32 v21, 0, v21
	v_sub_f32_e32 v157, v21, v22
	v_exp_f32_e64 v22, -|v24|
	v_max_f32_e32 v21, v24, v24
	v_min_f32_e32 v21, 0, v21
	v_exp_f32_e64 v23, -|v27|
	v_add_f32_e32 v22, 1.0, v22
	v_log_f32_e32 v22, v22
	v_exp_f32_e64 v24, -|v31|
	v_add_f32_e32 v23, 1.0, v23
	v_log_f32_e32 v23, v23
	v_sub_f32_e32 v158, v21, v22
	v_exp_f32_e64 v22, -|v25|
	v_max_f32_e32 v21, v25, v25
	v_min_f32_e32 v21, 0, v21
	v_add_f32_e32 v24, 1.0, v24
	v_add_f32_e32 v22, 1.0, v22
	v_log_f32_e32 v22, v22
	v_log_f32_e32 v24, v24
	v_mul_f32_e32 v20, 0x3d800000, v20
	v_sub_f32_e32 v159, v21, v22
	v_exp_f32_e64 v22, -|v26|
	v_max_f32_e32 v21, v26, v26
	v_min_f32_e32 v21, 0, v21
	v_fmamk_f32 v26, v157, 0x3d800000, v20
	v_add_f32_e32 v22, 1.0, v22
	v_log_f32_e32 v22, v22
	v_add_u32_e32 v157, 0x1000, v75
	v_sub_f32_e32 v21, v21, v22
	v_max_f32_e32 v22, v27, v27
	v_min_f32_e32 v22, 0, v22
	v_sub_f32_e32 v160, v22, v23
	v_exp_f32_e64 v23, -|v28|
	v_max_f32_e32 v22, v28, v28
	v_min_f32_e32 v22, 0, v22
	v_mul_f32_e32 v21, 0x3d800000, v21
	v_add_f32_e32 v23, 1.0, v23
	v_log_f32_e32 v23, v23
	v_fmamk_f32 v27, v158, 0x3d800000, v26
	v_fmamk_f32 v28, v159, 0x3d800000, v27
	ds_bpermute_b32 v158, v156, v28
	v_sub_f32_e32 v161, v22, v23
	v_exp_f32_e64 v23, -|v29|
	v_max_f32_e32 v22, v29, v29
	v_min_f32_e32 v22, 0, v22
	v_fmamk_f32 v29, v160, 0x3d800000, v21
	v_add_f32_e32 v23, 1.0, v23
	v_log_f32_e32 v23, v23
	s_nop 0
	v_sub_f32_e32 v163, v22, v23
	v_exp_f32_e64 v23, -|v30|
	v_max_f32_e32 v22, v30, v30
	v_min_f32_e32 v22, 0, v22
	v_fmamk_f32 v30, v161, 0x3d800000, v29
	v_add_f32_e32 v23, 1.0, v23
	v_log_f32_e32 v23, v23
	s_nop 0
	v_sub_f32_e32 v22, v22, v23
	v_max_f32_e32 v23, v31, v31
	v_min_f32_e32 v23, 0, v23
	v_sub_f32_e32 v164, v23, v24
	v_exp_f32_e64 v24, -|v32|
	v_max_f32_e32 v23, v32, v32
	v_min_f32_e32 v23, 0, v23
	v_mul_f32_e32 v22, 0x3d800000, v22
	v_add_f32_e32 v24, 1.0, v24
	v_log_f32_e32 v24, v24
	v_fmamk_f32 v32, v164, 0x3d800000, v22
	v_fmamk_f32 v31, v163, 0x3d800000, v30
	ds_bpermute_b32 v159, v156, v31
	v_sub_f32_e32 v165, v23, v24
	v_exp_f32_e64 v24, -|v33|
	v_max_f32_e32 v23, v33, v33
	v_min_f32_e32 v23, 0, v23
	v_fmamk_f32 v33, v165, 0x3d800000, v32
	v_add_f32_e32 v24, 1.0, v24
	v_log_f32_e32 v24, v24
	s_nop 0
	v_sub_f32_e32 v174, v23, v24
	v_fmamk_f32 v23, v18, 0x3d800000, v143
	v_fmamk_f32 v24, v19, 0x3d800000, v23
	v_fmamk_f32 v25, v147, 0x3d800000, v24
	ds_bpermute_b32 v149, v156, v25
	v_fmamk_f32 v147, v174, 0x3d800000, v33
	ds_bpermute_b32 v161, v156, v147
	s_waitcnt lgkmcnt(1)
	v_add_f32_e32 v18, v25, v149
	v_add_f32_e32 v160, 0, v18
	v_add_f32_e32 v18, v28, v158
	v_add_f32_e32 v163, v18, v160
	v_add_f32_e32 v18, v31, v159
	v_add_f32_e32 v164, v18, v163
	s_waitcnt lgkmcnt(0)
	v_add_f32_e32 v18, v147, v161
	v_add_f32_e32 v165, v18, v164
	ds_read2_b32 v[18:19], v157 offset1:2
	s_waitcnt lgkmcnt(0)
	v_mfma_f32_32x32x2_f32 v[2:17], v18, v173, v[2:17]
	v_mfma_f32_32x32x2_f32 v[2:17], v19, v172, v[2:17]
	ds_read2_b32 v[18:19], v157 offset0:4 offset1:6
	s_waitcnt lgkmcnt(0)
	v_mfma_f32_32x32x2_f32 v[2:17], v18, v171, v[2:17]
	v_mfma_f32_32x32x2_f32 v[2:17], v19, v170, v[2:17]
	ds_read2_b32 v[18:19], v157 offset0:8 offset1:10
	s_waitcnt lgkmcnt(0)
	v_mfma_f32_32x32x2_f32 v[2:17], v18, v169, v[2:17]
	v_mfma_f32_32x32x2_f32 v[2:17], v19, v168, v[2:17]
	ds_read2_b32 v[18:19], v157 offset0:12 offset1:14
	ds_write_b128 v79, v[34:37] offset:8192
	ds_write_b128 v79, v[38:41] offset:41984
	ds_write_b128 v83, v[42:45] offset:8192
	ds_write_b128 v83, v[46:49] offset:41984
	ds_write_b128 v79, v[50:53] offset:25088
	ds_write_b128 v79, v[54:57] offset:58880
	ds_write_b128 v89, v[58:61] offset:8192
	ds_write_b128 v89, v[62:65] offset:41984
	s_waitcnt lgkmcnt(8)
	v_mfma_f32_32x32x2_f32 v[2:17], v18, v167, v[2:17]
	v_mfma_f32_32x32x2_f32 v[2:17], v19, v166, v[2:17]
	s_nop 15
	s_nop 1
	v_max_f32_e32 v18, v17, v17
	v_exp_f32_e64 v17, -|v17|
	v_min_f32_e32 v18, 0, v18
	v_add_f32_e32 v17, 1.0, v17
	v_log_f32_e32 v17, v17
	s_nop 0
	v_sub_f32_e32 v17, v18, v17
	v_max_f32_e32 v18, v2, v2
	v_exp_f32_e64 v2, -|v2|
	v_min_f32_e32 v18, 0, v18
	v_add_f32_e32 v2, 1.0, v2
	v_log_f32_e32 v2, v2
	s_nop 0
	v_sub_f32_e32 v2, v18, v2
	v_mul_f32_e32 v18, 0x3d800000, v2
	v_max_f32_e32 v2, v3, v3
	v_exp_f32_e64 v3, -|v3|
	v_min_f32_e32 v2, 0, v2
	v_add_f32_e32 v3, 1.0, v3
	v_log_f32_e32 v3, v3
	s_nop 0
	v_sub_f32_e32 v2, v2, v3
	v_max_f32_e32 v3, v4, v4
	v_exp_f32_e64 v4, -|v4|
	v_min_f32_e32 v3, 0, v3
	v_add_f32_e32 v4, 1.0, v4
	v_log_f32_e32 v4, v4
	s_nop 0
	v_sub_f32_e32 v19, v3, v4
	v_exp_f32_e64 v4, -|v5|
	v_max_f32_e32 v3, v5, v5
	v_min_f32_e32 v3, 0, v3
	v_exp_f32_e64 v5, -|v7|
	v_add_f32_e32 v4, 1.0, v4
	v_log_f32_e32 v4, v4
	v_add_f32_e32 v5, 1.0, v5
	v_log_f32_e32 v5, v5
	v_sub_f32_e32 v166, v3, v4
	v_exp_f32_e64 v4, -|v6|
	v_max_f32_e32 v3, v6, v6
	v_min_f32_e32 v3, 0, v3
	v_exp_f32_e64 v6, -|v11|
	v_add_f32_e32 v4, 1.0, v4
	v_log_f32_e32 v4, v4
	v_add_f32_e32 v6, 1.0, v6
	v_log_f32_e32 v6, v6
	v_sub_f32_e32 v3, v3, v4
	v_max_f32_e32 v4, v7, v7
	v_min_f32_e32 v4, 0, v4
	v_sub_f32_e32 v167, v4, v5
	v_exp_f32_e64 v5, -|v8|
	v_max_f32_e32 v4, v8, v8
	v_min_f32_e32 v4, 0, v4
	v_exp_f32_e64 v7, -|v15|
	v_add_f32_e32 v5, 1.0, v5
	v_log_f32_e32 v5, v5
	v_mul_f32_e32 v3, 0x3d800000, v3
	v_add_f32_e32 v7, 1.0, v7
	v_log_f32_e32 v7, v7
	v_sub_f32_e32 v168, v4, v5
	v_exp_f32_e64 v5, -|v9|
	v_max_f32_e32 v4, v9, v9
	v_min_f32_e32 v4, 0, v4
	v_fmamk_f32 v9, v167, 0x3d800000, v3
	v_add_f32_e32 v5, 1.0, v5
	v_log_f32_e32 v5, v5
	s_nop 0
	v_sub_f32_e32 v169, v4, v5
	v_exp_f32_e64 v5, -|v10|
	v_max_f32_e32 v4, v10, v10
	v_min_f32_e32 v4, 0, v4
	v_fmamk_f32 v10, v168, 0x3d800000, v9
	v_add_f32_e32 v5, 1.0, v5
	v_log_f32_e32 v5, v5
	s_nop 0
	v_sub_f32_e32 v4, v4, v5
	v_max_f32_e32 v5, v11, v11
	v_min_f32_e32 v5, 0, v5
	v_sub_f32_e32 v170, v5, v6
	v_exp_f32_e64 v6, -|v12|
	v_max_f32_e32 v5, v12, v12
	v_min_f32_e32 v5, 0, v5
	v_mul_f32_e32 v4, 0x3d800000, v4
	v_add_f32_e32 v6, 1.0, v6
	v_log_f32_e32 v6, v6
	v_fmamk_f32 v11, v169, 0x3d800000, v10
	v_sub_f32_e32 v171, v5, v6
	v_exp_f32_e64 v6, -|v13|
	v_max_f32_e32 v5, v13, v13
	v_min_f32_e32 v5, 0, v5
	ds_bpermute_b32 v13, v156, v11
	v_add_f32_e32 v6, 1.0, v6
	v_log_f32_e32 v6, v6
	s_nop 0
	v_sub_f32_e32 v172, v5, v6
	v_exp_f32_e64 v6, -|v14|
	v_max_f32_e32 v5, v14, v14
	v_min_f32_e32 v5, 0, v5
	v_add_f32_e32 v6, 1.0, v6
	v_log_f32_e32 v6, v6
	s_nop 0
	v_sub_f32_e32 v5, v5, v6
	v_max_f32_e32 v6, v15, v15
	v_min_f32_e32 v6, 0, v6
	v_sub_f32_e32 v15, v6, v7
	v_exp_f32_e64 v7, -|v16|
	v_max_f32_e32 v6, v16, v16
	v_min_f32_e32 v6, 0, v6
	v_mul_f32_e32 v5, 0x3d800000, v5
	v_add_f32_e32 v7, 1.0, v7
	v_log_f32_e32 v7, v7
	v_fmamk_f32 v169, v15, 0x3d800000, v5
	v_sub_f32_e32 v16, v6, v7
	v_fmamk_f32 v6, v2, 0x3d800000, v18
	v_fmamk_f32 v7, v19, 0x3d800000, v6
	v_fmamk_f32 v8, v166, 0x3d800000, v7
	v_fmamk_f32 v166, v170, 0x3d800000, v4
	v_fmamk_f32 v167, v171, 0x3d800000, v166
	v_fmamk_f32 v170, v16, 0x3d800000, v169
	v_fmamk_f32 v168, v172, 0x3d800000, v167
	v_fmamk_f32 v171, v17, 0x3d800000, v170
	ds_bpermute_b32 v12, v156, v8
	ds_bpermute_b32 v14, v156, v168
	ds_bpermute_b32 v15, v156, v171
	v_exp_f32_e32 v17, v165
	s_and_saveexec_b64 s[68:69], s[0:1]
	s_cbranch_execz .LBB0_1211
	s_ashr_i32 vcc_hi, vcc_lo, 31
	s_lshl_b64 s[10:11], vcc, 10
	v_lshl_add_u64 v[172:173], v[84:85], 0, s[10:11]
	global_store_dword v[172:173], v17, off

.LBB0_1215:
	v_lshl_add_u64 v[2:3], s[76:77], 2, v[140:141]
	v_lshl_add_u64 v[4:5], v[144:145], 2, s[78:79]
	s_barrier
	global_load_dword v14, v[4:5], off nt
	v_lshl_add_u64 v[4:5], v[2:3], 0, v[68:69]
	global_load_dword v15, v[4:5], off nt
	v_add_co_u32_e32 v6, vcc, 0x3000, v4
	v_mov_b32_e32 v143, v69
	s_nop 0
	v_addc_co_u32_e32 v7, vcc, 0, v5, vcc
	global_load_dword v68, v[6:7], off nt
	v_add_co_u32_e32 v10, vcc, 0x9000, v4
	v_mov_b32_e32 v147, v69
	s_nop 0
	v_addc_co_u32_e32 v11, vcc, 0, v5, vcc
	v_add_co_u32_e32 v12, vcc, 0xf000, v4
	v_mov_b32_e32 v149, v69
	s_nop 0
	v_addc_co_u32_e32 v13, vcc, 0, v5, vcc
	v_lshl_add_u64 v[6:7], v[2:3], 0, v[142:143]
	v_add_co_u32_e32 v4, vcc, 0x15000, v4
	ds_read2_b32 v[144:145], v75 offset0:16 offset1:18
	v_lshl_add_u64 v[8:9], v[2:3], 0, v[146:147]
	v_lshl_add_u64 v[2:3], v[2:3], 0, v[148:149]
	v_addc_co_u32_e32 v5, vcc, 0, v5, vcc
	global_load_dword v146, v[6:7], off nt
	global_load_dword v147, v[10:11], off nt
	global_load_dword v148, v[8:9], off nt
	global_load_dword v149, v[12:13], off nt
	global_load_dword v182, v[2:3], off nt
	global_load_dword v183, v[4:5], off nt
	ds_read2_b32 v[142:143], v157 offset0:16 offset1:18
	s_add_i32 s76, s72, -1
	s_waitcnt vmcnt(8)
	v_mul_f32_e32 v2, 0x3fb8aa3b, v14
	v_mov_b32_e32 v3, v2
	s_waitcnt vmcnt(7)
	v_mul_f32_e32 v184, 0x3fb8aa3b, v15
	v_mov_b32_e32 v4, v2
	v_mov_b32_e32 v5, v2
	v_mov_b32_e32 v6, v2
	v_mov_b32_e32 v7, v2
	v_mov_b32_e32 v8, v2
	v_mov_b32_e32 v9, v2
	v_mov_b32_e32 v10, v2
	v_mov_b32_e32 v11, v2
	v_mov_b32_e32 v12, v2
	v_mov_b32_e32 v13, v2
	v_mov_b32_e32 v14, v2
	v_mov_b32_e32 v15, v2
	v_mov_b32_e32 v16, v2
	v_mov_b32_e32 v17, v2
	s_waitcnt vmcnt(6)
	v_mul_f32_e32 v68, 0x3fb8aa3b, v68
	s_waitcnt lgkmcnt(1)
	v_mfma_f32_32x32x2_f32 v[18:33], v144, v184, v[2:17]
	s_waitcnt lgkmcnt(0)
	v_mfma_f32_32x32x2_f32 v[2:17], v142, v184, v[2:17]
	v_mfma_f32_32x32x2_f32 v[18:33], v145, v68, v[18:33]
	ds_read2_b32 v[144:145], v157 offset0:20 offset1:22
	v_mfma_f32_32x32x2_f32 v[2:17], v143, v68, v[2:17]
	ds_read2_b32 v[142:143], v75 offset0:20 offset1:22
	s_waitcnt vmcnt(5)
	v_mul_f32_e32 v68, 0x3fb8aa3b, v146
	s_waitcnt vmcnt(2)
	v_mul_f32_e32 v146, 0x3fb8aa3b, v149
	s_waitcnt lgkmcnt(0)
	v_mfma_f32_32x32x2_f32 v[18:33], v142, v68, v[18:33]
	v_mfma_f32_32x32x2_f32 v[2:17], v144, v68, v[2:17]
	v_mul_f32_e32 v68, 0x3fb8aa3b, v147
	s_waitcnt vmcnt(1)
	v_mul_f32_e32 v147, 0x3fb8aa3b, v182
	s_waitcnt vmcnt(0)
	v_mul_f32_e32 v182, 0x3fb8aa3b, v183
	v_mfma_f32_32x32x2_f32 v[18:33], v143, v68, v[18:33]
	ds_read2_b32 v[142:143], v75 offset0:24 offset1:26
	v_mfma_f32_32x32x2_f32 v[2:17], v145, v68, v[2:17]
	v_mul_f32_e32 v68, 0x3fb8aa3b, v148
	ds_read2_b32 v[144:145], v157 offset0:24 offset1:26
	s_waitcnt lgkmcnt(1)
	v_mfma_f32_32x32x2_f32 v[18:33], v142, v68, v[18:33]
	v_mfma_f32_32x32x2_f32 v[18:33], v143, v146, v[18:33]
	ds_read2_b32 v[142:143], v75 offset0:28 offset1:30
	s_waitcnt lgkmcnt(0)
	v_mfma_f32_32x32x2_f32 v[18:33], v142, v147, v[18:33]
	v_mfma_f32_32x32x2_f32 v[18:33], v143, v182, v[18:33]
	v_mfma_f32_32x32x2_f32 v[2:17], v144, v68, v[2:17]
	s_nop 15
	s_nop 0
	v_max_f32_e32 v68, v33, v33
	v_exp_f32_e64 v33, -|v33|
	v_max_f32_e32 v142, v18, v18
	v_exp_f32_e64 v18, -|v18|
	v_max_f32_e32 v143, v19, v19
	v_exp_f32_e64 v19, -|v19|
	v_max_f32_e32 v148, v21, v21
	v_exp_f32_e64 v21, -|v21|
	v_max_f32_e32 v149, v22, v22
	v_exp_f32_e64 v22, -|v22|
	v_add_f32_e32 v33, 1.0, v33
	v_add_f32_e32 v18, 1.0, v18
	v_add_f32_e32 v19, 1.0, v19
	v_add_f32_e32 v21, 1.0, v21
	v_add_f32_e32 v22, 1.0, v22
	v_mfma_f32_32x32x2_f32 v[2:17], v145, v146, v[2:17]
	v_log_f32_e32 v33, v33
	v_log_f32_e32 v18, v18
	v_log_f32_e32 v19, v19
	v_log_f32_e32 v21, v21
	v_log_f32_e32 v22, v22
	v_min_f32_e32 v68, 0, v68
	v_min_f32_e32 v142, 0, v142
	v_min_f32_e32 v143, 0, v143
	v_min_f32_e32 v148, 0, v148
	v_min_f32_e32 v149, 0, v149
	v_sub_f32_e32 v33, v68, v33
	v_sub_f32_e32 v68, v142, v18
	v_sub_f32_e32 v142, v143, v19
	v_sub_f32_e32 v19, v148, v21
	v_sub_f32_e32 v193, v149, v22
	ds_read2_b32 v[148:149], v157 offset0:28 offset1:30
	s_waitcnt lgkmcnt(0)
	v_mfma_f32_32x32x2_f32 v[2:17], v148, v147, v[2:17]
	v_max_f32_e32 v144, v20, v20
	v_exp_f32_e64 v20, -|v20|
	v_max_f32_e32 v183, v23, v23
	v_exp_f32_e64 v23, -|v23|
	v_max_f32_e32 v189, v29, v29
	v_exp_f32_e64 v29, -|v29|
	v_max_f32_e32 v185, v25, v25
	v_exp_f32_e64 v25, -|v25|
	v_max_f32_e32 v188, v28, v28
	v_exp_f32_e64 v28, -|v28|
	v_exp_f32_e64 v191, -|v31|
	v_add_f32_e32 v20, 1.0, v20
	v_add_f32_e32 v23, 1.0, v23
	v_add_f32_e32 v29, 1.0, v29
	v_log_f32_e32 v20, v20
	v_log_f32_e32 v23, v23
	v_log_f32_e32 v29, v29
	v_max_f32_e32 v184, v24, v24
	v_exp_f32_e64 v24, -|v24|
	v_add_f32_e32 v25, 1.0, v25
	v_add_f32_e32 v28, 1.0, v28
	v_add_f32_e32 v191, 1.0, v191
	v_max_f32_e32 v186, v26, v26
	v_exp_f32_e64 v26, -|v26|
	v_max_f32_e32 v187, v27, v27
	v_exp_f32_e64 v27, -|v27|
	v_exp_f32_e64 v192, -|v32|
	v_min_f32_e32 v144, 0, v144
	v_min_f32_e32 v183, 0, v183
	v_min_f32_e32 v189, 0, v189
	v_log_f32_e32 v25, v25
	v_log_f32_e32 v28, v28
	v_log_f32_e32 v191, v191
	v_sub_f32_e32 v143, v144, v20
	v_sub_f32_e32 v144, v183, v23
	v_sub_f32_e32 v23, v189, v29
	v_max_f32_e32 v190, v30, v30
	v_exp_f32_e64 v30, -|v30|
	v_add_f32_e32 v24, 1.0, v24
	v_mul_f32_e32 v21, 0x3d800000, v19
	v_mul_f32_e32 v19, 0x3d800000, v23
	v_max_f32_e32 v23, v31, v31
	v_mfma_f32_32x32x2_f32 v[2:17], v149, v182, v[2:17]
	v_min_f32_e32 v185, 0, v185
	v_min_f32_e32 v188, 0, v188
	v_log_f32_e32 v24, v24
	v_min_f32_e32 v23, 0, v23
	v_add_f32_e32 v26, 1.0, v26
	v_add_f32_e32 v27, 1.0, v27
	v_sub_f32_e32 v20, v185, v25
	v_sub_f32_e32 v25, v188, v28
	v_sub_f32_e32 v28, v23, v191
	v_add_f32_e32 v23, 1.0, v192
	v_log_f32_e32 v26, v26
	v_log_f32_e32 v27, v27
	v_log_f32_e32 v23, v23
	v_min_f32_e32 v184, 0, v184
	v_add_f32_e32 v30, 1.0, v30
	v_log_f32_e32 v30, v30
	v_sub_f32_e32 v22, v184, v24
	v_max_f32_e32 v24, v32, v32
	v_min_f32_e32 v186, 0, v186
	v_min_f32_e32 v187, 0, v187
	v_min_f32_e32 v24, 0, v24
	v_sub_f32_e32 v183, v186, v26
	v_sub_f32_e32 v26, v187, v27
	v_mul_f32_e32 v18, 0x3d800000, v33
	v_sub_f32_e32 v27, v24, v23
	v_min_f32_e32 v190, 0, v190
	v_fmamk_f32 v27, v27, 0x3d800000, v18
	v_sub_f32_e32 v29, v190, v30
	v_mul_f32_e32 v20, 0x3d800000, v20
	v_fmamk_f32 v25, v25, 0x3d800000, v19
	v_fmamk_f32 v28, v28, 0x3d800000, v27
	v_fmamk_f32 v23, v143, 0x3d800000, v21
	v_fmamk_f32 v22, v22, 0x3d800000, v20
	v_fmamk_f32 v26, v26, 0x3d800000, v25
	v_fmamk_f32 v29, v29, 0x3d800000, v28
	v_fmamk_f32 v30, v142, 0x3d800000, v23
	v_fmamk_f32 v24, v144, 0x3d800000, v22
	ds_bpermute_b32 v143, v156, v29
	v_fmamk_f32 v33, v183, 0x3d800000, v26
	v_fmamk_f32 v32, v68, 0x3d800000, v30
	ds_bpermute_b32 v144, v156, v33
	v_fmamk_f32 v68, v193, 0x3d800000, v24
	ds_bpermute_b32 v146, v156, v68
	ds_bpermute_b32 v142, v156, v32
	s_waitcnt lgkmcnt(3)
	v_add_f32_e32 v31, v29, v143
	v_exp_f32_e64 v149, -|v17|
	v_add_f32_e32 v145, 0, v31
	s_waitcnt lgkmcnt(2)
	v_add_f32_e32 v31, v33, v144
	v_add_f32_e32 v147, v31, v145
	s_waitcnt lgkmcnt(1)
	v_add_f32_e32 v31, v68, v146
	v_add_f32_e32 v148, v31, v147
	s_waitcnt lgkmcnt(0)
	v_add_f32_e32 v31, v32, v142
	v_add_f32_e32 v185, v31, v148
	v_add_f32_e32 v31, 1.0, v149
	v_log_f32_e32 v31, v31
	v_exp_f32_e64 v149, -|v2|
	v_max_f32_e32 v17, v17, v17
	v_min_f32_e32 v17, 0, v17
	v_sub_f32_e32 v17, v17, v31
	v_mul_f32_e32 v31, 0x3d800000, v17
	v_add_f32_e32 v17, 1.0, v149
	v_log_f32_e32 v17, v17
	v_exp_f32_e64 v149, -|v3|
	v_max_f32_e32 v2, v2, v2
	v_min_f32_e32 v2, 0, v2
	v_sub_f32_e32 v2, v2, v17
	v_add_f32_e32 v17, 1.0, v149
	v_log_f32_e32 v17, v17
	v_exp_f32_e64 v149, -|v4|
	v_max_f32_e32 v3, v3, v3
	v_min_f32_e32 v3, 0, v3
	v_sub_f32_e32 v17, v3, v17
	v_add_f32_e32 v3, 1.0, v149
	v_log_f32_e32 v3, v3
	v_exp_f32_e64 v149, -|v5|
	v_max_f32_e32 v4, v4, v4
	v_min_f32_e32 v4, 0, v4
	v_sub_f32_e32 v157, v4, v3
	v_add_f32_e32 v3, 1.0, v149
	v_log_f32_e32 v3, v3
	v_max_f32_e32 v4, v5, v5
	v_exp_f32_e64 v5, -|v6|
	v_min_f32_e32 v4, 0, v4
	v_sub_f32_e32 v3, v4, v3
	v_max_f32_e32 v6, v6, v6
	v_add_f32_e32 v4, 1.0, v5
	v_log_f32_e32 v4, v4
	v_exp_f32_e64 v5, -|v7|
	v_min_f32_e32 v6, 0, v6
	v_mul_f32_e32 v3, 0x3d800000, v3
	v_sub_f32_e32 v149, v6, v4
	v_add_f32_e32 v4, 1.0, v5
	v_log_f32_e32 v4, v4
	v_exp_f32_e64 v5, -|v8|
	v_max_f32_e32 v6, v7, v7
	v_min_f32_e32 v6, 0, v6
	v_sub_f32_e32 v182, v6, v4
	v_add_f32_e32 v4, 1.0, v5
	v_log_f32_e32 v4, v4
	v_exp_f32_e64 v5, -|v9|
	v_max_f32_e32 v6, v8, v8
	v_min_f32_e32 v6, 0, v6
	v_sub_f32_e32 v7, v6, v4
	v_add_f32_e32 v4, 1.0, v5
	v_log_f32_e32 v4, v4
	v_exp_f32_e64 v6, -|v10|
	v_max_f32_e32 v5, v9, v9
	v_min_f32_e32 v5, 0, v5
	v_sub_f32_e32 v4, v5, v4
	v_add_f32_e32 v5, 1.0, v6
	v_log_f32_e32 v5, v5
	v_exp_f32_e64 v6, -|v11|
	v_max_f32_e32 v8, v10, v10
	v_min_f32_e32 v8, 0, v8
	v_sub_f32_e32 v183, v8, v5
	v_add_f32_e32 v5, 1.0, v6
	v_log_f32_e32 v5, v5
	v_exp_f32_e64 v6, -|v12|
	v_max_f32_e32 v8, v11, v11
	v_min_f32_e32 v8, 0, v8
	v_sub_f32_e32 v184, v8, v5
	v_add_f32_e32 v5, 1.0, v6
	v_log_f32_e32 v5, v5
	v_exp_f32_e64 v6, -|v13|
	v_max_f32_e32 v8, v12, v12
	v_min_f32_e32 v8, 0, v8
	v_sub_f32_e32 v8, v8, v5
	v_add_f32_e32 v5, 1.0, v6
	v_log_f32_e32 v5, v5
	v_exp_f32_e64 v9, -|v14|
	v_max_f32_e32 v6, v13, v13
	v_min_f32_e32 v6, 0, v6
	v_sub_f32_e32 v5, v6, v5
	v_add_f32_e32 v6, 1.0, v9
	v_log_f32_e32 v6, v6
	v_max_f32_e32 v9, v14, v14
	v_exp_f32_e64 v10, -|v15|
	v_min_f32_e32 v9, 0, v9
	v_sub_f32_e32 v186, v9, v6
	v_exp_f32_e64 v9, -|v16|
	v_add_f32_e32 v10, 1.0, v10
	v_log_f32_e32 v10, v10
	v_max_f32_e32 v6, v15, v15
	v_add_f32_e32 v9, 1.0, v9
	v_log_f32_e32 v9, v9
	v_min_f32_e32 v6, 0, v6
	v_mul_f32_e32 v4, 0x3d800000, v4
	v_sub_f32_e32 v187, v6, v10
	v_max_f32_e32 v6, v16, v16
	v_min_f32_e32 v6, 0, v6
	v_fmamk_f32 v7, v7, 0x3d800000, v4
	v_mul_f32_e32 v5, 0x3d800000, v5
	v_sub_f32_e32 v16, v6, v9
	v_fmamk_f32 v10, v182, 0x3d800000, v7
	v_fmamk_f32 v6, v157, 0x3d800000, v3
	v_fmamk_f32 v12, v149, 0x3d800000, v10
	v_fmamk_f32 v8, v8, 0x3d800000, v5
	v_fmamk_f32 v149, v16, 0x3d800000, v31
	v_fmamk_f32 v9, v17, 0x3d800000, v6
	v_fmamk_f32 v157, v184, 0x3d800000, v8
	v_fmamk_f32 v182, v187, 0x3d800000, v149
	v_fmamk_f32 v11, v2, 0x3d800000, v9
	v_fmamk_f32 v183, v183, 0x3d800000, v157
	v_fmamk_f32 v184, v186, 0x3d800000, v182
	ds_bpermute_b32 v14, v156, v11
	ds_bpermute_b32 v13, v156, v12
	ds_bpermute_b32 v15, v156, v183
	ds_bpermute_b32 v16, v156, v184
	v_exp_f32_e32 v17, v185
	ds_write_b128 v79, v[34:37] offset:8192
	ds_write_b128 v79, v[38:41] offset:41984
	ds_write_b128 v83, v[42:45] offset:8192
	ds_write_b128 v83, v[46:49] offset:41984
	ds_write_b128 v79, v[50:53] offset:25088
	ds_write_b128 v79, v[54:57] offset:58880
	ds_write_b128 v89, v[58:61] offset:8192
	ds_write_b128 v89, v[62:65] offset:41984
	s_and_saveexec_b64 vcc, s[0:1]
	s_cbranch_execz .LBB0_1217
	s_ashr_i32 s77, s76, 31
	s_lshl_b64 s[10:11], s[76:77], 10
	v_lshl_add_u64 v[34:35], v[84:85], 0, s[10:11]
	global_store_dword v[34:35], v17, off
